# v67 + nt hint on the gate / t2 output stores of the scan-independent GEMMs and on the final output stores of phase 5b
# baseline (speedup 1.0000x reference)
.LBB0_1005:
	s_or_b64 exec, exec, s[34:35]
	s_lshl_b32 s3, s69, 2
	s_add_i32 s3, s3, 0
	s_add_i32 s3, s3, 0x21000
	v_lshl_add_u32 v133, v133, 2, s3
	s_lshl_b32 s3, s68, 5
	s_lshl_b32 s20, s30, 8
	s_or_b32 s21, s20, 0x80
	s_waitcnt vmcnt(0) lgkmcnt(0)
	s_barrier
	v_lshl_add_u32 v128, v132, 3, s3
	v_add_u32_e32 v130, s20, v128
	v_add_u32_e32 v128, s21, v128
	v_ashrrev_i32_e32 v131, 31, v130
	v_ashrrev_i32_e32 v129, 31, v128
	s_and_saveexec_b64 s[20:21], s[4:5]
	s_cbranch_execz .LBB0_1013
	v_readlane_b32 s80, v255, 0
	v_readlane_b32 s84, v255, 4
	v_readlane_b32 s85, v255, 5
	v_readlane_b32 s86, v255, 6
	v_readlane_b32 s87, v255, 7
	s_mov_b64 s[44:45], s[84:85]
	v_lshl_add_u64 v[146:147], v[130:131], 2, s[44:45]
	global_load_dwordx4 v[142:145], v[146:147], off
	ds_read_b32 v132, v133
	v_lshlrev_b32_e32 v134, 12, v134
	s_mov_b64 s[46:47], s[86:87]
	v_lshl_add_u32 v148, v130, 2, v134
	v_readlane_b32 s81, v255, 1
	s_waitcnt lgkmcnt(0)
	v_pk_mul_f32 v[126:127], v[126:127], v[132:133] op_sel_hi:[1,0]
	v_pk_mul_f32 v[124:125], v[124:125], v[132:133] op_sel_hi:[1,0]
	v_pk_mul_f32 v[118:119], v[118:119], v[132:133] op_sel_hi:[1,0]
	v_pk_mul_f32 v[116:117], v[116:117], v[132:133] op_sel_hi:[1,0]
	v_pk_mul_f32 v[122:123], v[122:123], v[132:133] op_sel_hi:[1,0]
	v_pk_mul_f32 v[120:121], v[120:121], v[132:133] op_sel_hi:[1,0]
	v_pk_mul_f32 v[114:115], v[114:115], v[132:133] op_sel_hi:[1,0]
	v_pk_mul_f32 v[112:113], v[112:113], v[132:133] op_sel_hi:[1,0]
	v_readlane_b32 s82, v255, 2
	v_readlane_b32 s83, v255, 3
	s_waitcnt vmcnt(0)
	v_pk_mul_f32 v[126:127], v[144:145], v[126:127]
	v_pk_mul_f32 v[124:125], v[142:143], v[124:125]
	global_store_dwordx4 v148, v[124:127], s[46:47] nt
	global_load_dwordx4 v[124:127], v[146:147], off offset:16
	v_lshl_add_u64 v[142:143], v[128:129], 2, s[44:45]
	s_waitcnt vmcnt(0)
	v_pk_mul_f32 v[118:119], v[118:119], v[126:127]
	v_pk_mul_f32 v[116:117], v[116:117], v[124:125]
	global_store_dwordx4 v148, v[116:119], s[46:47] offset:16 nt
	global_load_dwordx4 v[116:119], v[142:143], off
	v_lshl_add_u32 v124, v128, 2, v134
	s_waitcnt vmcnt(0)
	v_pk_mul_f32 v[118:119], v[122:123], v[118:119]
	v_pk_mul_f32 v[116:117], v[120:121], v[116:117]
	global_store_dwordx4 v124, v[116:119], s[46:47] nt
	global_load_dwordx4 v[116:119], v[142:143], off offset:16
	s_waitcnt vmcnt(0)
	v_pk_mul_f32 v[114:115], v[114:115], v[118:119]
	v_pk_mul_f32 v[112:113], v[112:113], v[116:117]
	global_store_dwordx4 v124, v[112:115], s[46:47] offset:16 nt
	s_or_b64 exec, exec, s[20:21]
	s_and_saveexec_b64 s[4:5], s[6:7]
	s_cbranch_execnz .LBB0_1014

.LBB0_1008:
	v_readlane_b32 s80, v255, 0
	v_readlane_b32 s84, v255, 4
	v_readlane_b32 s85, v255, 5
	v_readlane_b32 s86, v255, 6
	v_readlane_b32 s87, v255, 7
	s_mov_b64 s[44:45], s[84:85]
	v_lshl_add_u64 v[100:101], v[130:131], 2, s[44:45]
	global_load_dwordx4 v[96:99], v[100:101], off
	ds_read_b32 v102, v133 offset:128
	v_lshlrev_b32_e32 v103, 12, v136
	s_mov_b64 s[46:47], s[86:87]
	v_lshl_add_u32 v104, v130, 2, v103
	v_readlane_b32 s81, v255, 1
	s_waitcnt lgkmcnt(0)
	v_pk_mul_f32 v[94:95], v[94:95], v[102:103] op_sel_hi:[1,0]
	v_pk_mul_f32 v[92:93], v[92:93], v[102:103] op_sel_hi:[1,0]
	v_pk_mul_f32 v[86:87], v[86:87], v[102:103] op_sel_hi:[1,0]
	v_pk_mul_f32 v[84:85], v[84:85], v[102:103] op_sel_hi:[1,0]
	v_pk_mul_f32 v[90:91], v[90:91], v[102:103] op_sel_hi:[1,0]
	v_pk_mul_f32 v[88:89], v[88:89], v[102:103] op_sel_hi:[1,0]
	v_pk_mul_f32 v[82:83], v[82:83], v[102:103] op_sel_hi:[1,0]
	v_pk_mul_f32 v[80:81], v[80:81], v[102:103] op_sel_hi:[1,0]
	v_readlane_b32 s82, v255, 2
	v_readlane_b32 s83, v255, 3
	s_waitcnt vmcnt(0)
	v_pk_mul_f32 v[94:95], v[98:99], v[94:95]
	v_pk_mul_f32 v[92:93], v[96:97], v[92:93]
	global_store_dwordx4 v104, v[92:95], s[46:47] nt
	global_load_dwordx4 v[92:95], v[100:101], off offset:16
	v_lshl_add_u64 v[96:97], v[128:129], 2, s[44:45]
	s_waitcnt vmcnt(0)
	v_pk_mul_f32 v[86:87], v[86:87], v[94:95]
	v_pk_mul_f32 v[84:85], v[84:85], v[92:93]
	global_store_dwordx4 v104, v[84:87], s[46:47] offset:16 nt
	global_load_dwordx4 v[84:87], v[96:97], off
	v_lshl_add_u32 v92, v128, 2, v103
	s_waitcnt vmcnt(0)
	v_pk_mul_f32 v[86:87], v[90:91], v[86:87]
	v_pk_mul_f32 v[84:85], v[88:89], v[84:85]
	global_store_dwordx4 v92, v[84:87], s[46:47] nt
	global_load_dwordx4 v[84:87], v[96:97], off offset:16
	s_waitcnt vmcnt(0)
	v_pk_mul_f32 v[82:83], v[82:83], v[86:87]
	v_pk_mul_f32 v[80:81], v[80:81], v[84:85]
	global_store_dwordx4 v92, v[80:83], s[46:47] offset:16 nt
	s_or_b64 exec, exec, s[4:5]
	s_and_saveexec_b64 s[4:5], s[10:11]
	s_cbranch_execnz .LBB0_1016

.LBB0_1010:
	v_readlane_b32 s80, v255, 0
	v_readlane_b32 s84, v255, 4
	v_readlane_b32 s85, v255, 5
	v_readlane_b32 s86, v255, 6
	v_readlane_b32 s87, v255, 7
	s_mov_b64 s[8:9], s[84:85]
	v_lshl_add_u64 v[68:69], v[130:131], 2, s[8:9]
	global_load_dwordx4 v[64:67], v[68:69], off
	ds_read_b32 v70, v133 offset:512
	v_lshlrev_b32_e32 v71, 12, v138
	s_mov_b64 s[10:11], s[86:87]
	v_lshl_add_u32 v72, v130, 2, v71
	v_readlane_b32 s81, v255, 1
	s_waitcnt lgkmcnt(0)
	v_pk_mul_f32 v[62:63], v[62:63], v[70:71] op_sel_hi:[1,0]
	v_pk_mul_f32 v[60:61], v[60:61], v[70:71] op_sel_hi:[1,0]
	v_pk_mul_f32 v[54:55], v[54:55], v[70:71] op_sel_hi:[1,0]
	v_pk_mul_f32 v[52:53], v[52:53], v[70:71] op_sel_hi:[1,0]
	v_pk_mul_f32 v[58:59], v[58:59], v[70:71] op_sel_hi:[1,0]
	v_pk_mul_f32 v[56:57], v[56:57], v[70:71] op_sel_hi:[1,0]
	v_pk_mul_f32 v[50:51], v[50:51], v[70:71] op_sel_hi:[1,0]
	v_pk_mul_f32 v[48:49], v[48:49], v[70:71] op_sel_hi:[1,0]
	v_readlane_b32 s82, v255, 2
	v_readlane_b32 s83, v255, 3
	s_waitcnt vmcnt(0)
	v_pk_mul_f32 v[62:63], v[66:67], v[62:63]
	v_pk_mul_f32 v[60:61], v[64:65], v[60:61]
	global_store_dwordx4 v72, v[60:63], s[10:11] nt
	global_load_dwordx4 v[60:63], v[68:69], off offset:16
	v_lshl_add_u64 v[64:65], v[128:129], 2, s[8:9]
	s_waitcnt vmcnt(0)
	v_pk_mul_f32 v[54:55], v[54:55], v[62:63]
	v_pk_mul_f32 v[52:53], v[52:53], v[60:61]
	global_store_dwordx4 v72, v[52:55], s[10:11] offset:16 nt
	global_load_dwordx4 v[52:55], v[64:65], off
	v_lshl_add_u32 v60, v128, 2, v71
	s_waitcnt vmcnt(0)
	v_pk_mul_f32 v[54:55], v[58:59], v[54:55]
	v_pk_mul_f32 v[52:53], v[56:57], v[52:53]
	global_store_dwordx4 v60, v[52:55], s[10:11] nt
	global_load_dwordx4 v[52:55], v[64:65], off offset:16
	s_waitcnt vmcnt(0)
	v_pk_mul_f32 v[50:51], v[50:51], v[54:55]
	v_pk_mul_f32 v[48:49], v[48:49], v[52:53]
	global_store_dwordx4 v60, v[48:51], s[10:11] offset:16 nt
	s_or_b64 exec, exec, s[4:5]
	s_and_saveexec_b64 s[4:5], s[14:15]
	s_cbranch_execnz .LBB0_1018

.LBB0_1012:
	v_readlane_b32 s8, v255, 0
	v_readlane_b32 s9, v255, 1
	v_readlane_b32 s10, v255, 2
	v_readlane_b32 s11, v255, 3
	v_readlane_b32 s12, v255, 4
	v_readlane_b32 s13, v255, 5
	v_readlane_b32 s14, v255, 6
	v_readlane_b32 s15, v255, 7
	s_mov_b64 s[8:9], s[12:13]
	v_lshl_add_u64 v[36:37], v[130:131], 2, s[8:9]
	global_load_dwordx4 v[32:35], v[36:37], off
	ds_read_b32 v38, v133 offset:640
	v_lshlrev_b32_e32 v39, 12, v140
	s_mov_b64 s[10:11], s[14:15]
	v_lshl_add_u32 v40, v130, 2, v39
	s_waitcnt lgkmcnt(0)
	v_pk_mul_f32 v[30:31], v[30:31], v[38:39] op_sel_hi:[1,0]
	v_pk_mul_f32 v[28:29], v[28:29], v[38:39] op_sel_hi:[1,0]
	v_pk_mul_f32 v[22:23], v[22:23], v[38:39] op_sel_hi:[1,0]
	v_pk_mul_f32 v[20:21], v[20:21], v[38:39] op_sel_hi:[1,0]
	v_pk_mul_f32 v[26:27], v[26:27], v[38:39] op_sel_hi:[1,0]
	v_pk_mul_f32 v[24:25], v[24:25], v[38:39] op_sel_hi:[1,0]
	v_pk_mul_f32 v[18:19], v[18:19], v[38:39] op_sel_hi:[1,0]
	v_pk_mul_f32 v[16:17], v[16:17], v[38:39] op_sel_hi:[1,0]
	s_waitcnt vmcnt(0)
	v_pk_mul_f32 v[30:31], v[34:35], v[30:31]
	v_pk_mul_f32 v[28:29], v[32:33], v[28:29]
	global_store_dwordx4 v40, v[28:31], s[10:11] nt
	global_load_dwordx4 v[28:31], v[36:37], off offset:16
	v_lshl_add_u64 v[32:33], v[128:129], 2, s[8:9]
	s_waitcnt vmcnt(0)
	v_pk_mul_f32 v[22:23], v[22:23], v[30:31]
	v_pk_mul_f32 v[20:21], v[20:21], v[28:29]
	global_store_dwordx4 v40, v[20:23], s[10:11] offset:16 nt
	global_load_dwordx4 v[20:23], v[32:33], off
	v_lshl_add_u32 v28, v128, 2, v39
	s_waitcnt vmcnt(0)
	v_pk_mul_f32 v[22:23], v[26:27], v[22:23]
	v_pk_mul_f32 v[20:21], v[24:25], v[20:21]
	global_store_dwordx4 v28, v[20:23], s[10:11] nt
	global_load_dwordx4 v[20:23], v[32:33], off offset:16
	s_waitcnt vmcnt(0)
	v_pk_mul_f32 v[18:19], v[18:19], v[22:23]
	v_pk_mul_f32 v[16:17], v[16:17], v[20:21]
	global_store_dwordx4 v28, v[16:19], s[10:11] offset:16 nt
	s_or_b64 exec, exec, s[4:5]
	s_and_saveexec_b64 s[4:5], s[18:19]
	s_cbranch_execnz .LBB0_1020
	s_branch .LBB0_1021

.LBB0_1014:
	v_readlane_b32 s80, v255, 0
	v_readlane_b32 s84, v255, 4
	v_readlane_b32 s85, v255, 5
	v_readlane_b32 s86, v255, 6
	v_readlane_b32 s87, v255, 7
	s_mov_b64 s[44:45], s[84:85]
	v_lshl_add_u64 v[116:117], v[130:131], 2, s[44:45]
	global_load_dwordx4 v[112:115], v[116:117], off
	ds_read_b32 v118, v133 offset:64
	v_lshlrev_b32_e32 v119, 12, v135
	s_mov_b64 s[46:47], s[86:87]
	v_lshl_add_u32 v120, v130, 2, v119
	v_readlane_b32 s81, v255, 1
	s_waitcnt lgkmcnt(0)
	v_pk_mul_f32 v[110:111], v[110:111], v[118:119] op_sel_hi:[1,0]
	v_pk_mul_f32 v[108:109], v[108:109], v[118:119] op_sel_hi:[1,0]
	v_pk_mul_f32 v[102:103], v[102:103], v[118:119] op_sel_hi:[1,0]
	v_pk_mul_f32 v[100:101], v[100:101], v[118:119] op_sel_hi:[1,0]
	v_pk_mul_f32 v[106:107], v[106:107], v[118:119] op_sel_hi:[1,0]
	v_pk_mul_f32 v[104:105], v[104:105], v[118:119] op_sel_hi:[1,0]
	v_pk_mul_f32 v[98:99], v[98:99], v[118:119] op_sel_hi:[1,0]
	v_pk_mul_f32 v[96:97], v[96:97], v[118:119] op_sel_hi:[1,0]
	v_readlane_b32 s82, v255, 2
	v_readlane_b32 s83, v255, 3
	s_waitcnt vmcnt(0)
	v_pk_mul_f32 v[110:111], v[114:115], v[110:111]
	v_pk_mul_f32 v[108:109], v[112:113], v[108:109]
	global_store_dwordx4 v120, v[108:111], s[46:47] nt
	global_load_dwordx4 v[108:111], v[116:117], off offset:16
	v_lshl_add_u64 v[112:113], v[128:129], 2, s[44:45]
	s_waitcnt vmcnt(0)
	v_pk_mul_f32 v[102:103], v[102:103], v[110:111]
	v_pk_mul_f32 v[100:101], v[100:101], v[108:109]
	global_store_dwordx4 v120, v[100:103], s[46:47] offset:16 nt
	global_load_dwordx4 v[100:103], v[112:113], off
	v_lshl_add_u32 v108, v128, 2, v119
	s_waitcnt vmcnt(0)
	v_pk_mul_f32 v[102:103], v[106:107], v[102:103]
	v_pk_mul_f32 v[100:101], v[104:105], v[100:101]
	global_store_dwordx4 v108, v[100:103], s[46:47] nt
	global_load_dwordx4 v[100:103], v[112:113], off offset:16
	s_waitcnt vmcnt(0)
	v_pk_mul_f32 v[98:99], v[98:99], v[102:103]
	v_pk_mul_f32 v[96:97], v[96:97], v[100:101]
	global_store_dwordx4 v108, v[96:99], s[46:47] offset:16 nt
	s_or_b64 exec, exec, s[4:5]
	s_and_saveexec_b64 s[4:5], s[8:9]
	s_cbranch_execnz .LBB0_1008

.LBB0_1016:
	v_readlane_b32 s80, v255, 0
	v_readlane_b32 s84, v255, 4
	v_readlane_b32 s85, v255, 5
	v_readlane_b32 s86, v255, 6
	v_readlane_b32 s87, v255, 7
	s_mov_b64 s[8:9], s[84:85]
	v_lshl_add_u64 v[84:85], v[130:131], 2, s[8:9]
	global_load_dwordx4 v[80:83], v[84:85], off
	ds_read_b32 v86, v133 offset:192
	v_lshlrev_b32_e32 v87, 12, v137
	s_mov_b64 s[10:11], s[86:87]
	v_lshl_add_u32 v88, v130, 2, v87
	v_readlane_b32 s81, v255, 1
	s_waitcnt lgkmcnt(0)
	v_pk_mul_f32 v[78:79], v[78:79], v[86:87] op_sel_hi:[1,0]
	v_pk_mul_f32 v[76:77], v[76:77], v[86:87] op_sel_hi:[1,0]
	v_pk_mul_f32 v[70:71], v[70:71], v[86:87] op_sel_hi:[1,0]
	v_pk_mul_f32 v[68:69], v[68:69], v[86:87] op_sel_hi:[1,0]
	v_pk_mul_f32 v[74:75], v[74:75], v[86:87] op_sel_hi:[1,0]
	v_pk_mul_f32 v[72:73], v[72:73], v[86:87] op_sel_hi:[1,0]
	v_pk_mul_f32 v[66:67], v[66:67], v[86:87] op_sel_hi:[1,0]
	v_pk_mul_f32 v[64:65], v[64:65], v[86:87] op_sel_hi:[1,0]
	v_readlane_b32 s82, v255, 2
	v_readlane_b32 s83, v255, 3
	s_waitcnt vmcnt(0)
	v_pk_mul_f32 v[78:79], v[82:83], v[78:79]
	v_pk_mul_f32 v[76:77], v[80:81], v[76:77]
	global_store_dwordx4 v88, v[76:79], s[10:11] nt
	global_load_dwordx4 v[76:79], v[84:85], off offset:16
	v_lshl_add_u64 v[80:81], v[128:129], 2, s[8:9]
	s_waitcnt vmcnt(0)
	v_pk_mul_f32 v[70:71], v[70:71], v[78:79]
	v_pk_mul_f32 v[68:69], v[68:69], v[76:77]
	global_store_dwordx4 v88, v[68:71], s[10:11] offset:16 nt
	global_load_dwordx4 v[68:71], v[80:81], off
	v_lshl_add_u32 v76, v128, 2, v87
	s_waitcnt vmcnt(0)
	v_pk_mul_f32 v[70:71], v[74:75], v[70:71]
	v_pk_mul_f32 v[68:69], v[72:73], v[68:69]
	global_store_dwordx4 v76, v[68:71], s[10:11] nt
	global_load_dwordx4 v[68:71], v[80:81], off offset:16
	s_waitcnt vmcnt(0)
	v_pk_mul_f32 v[66:67], v[66:67], v[70:71]
	v_pk_mul_f32 v[64:65], v[64:65], v[68:69]
	global_store_dwordx4 v76, v[64:67], s[10:11] offset:16 nt
	s_or_b64 exec, exec, s[4:5]
	s_and_saveexec_b64 s[4:5], s[12:13]
	s_cbranch_execnz .LBB0_1010

.LBB0_1018:
	v_readlane_b32 s8, v255, 0
	v_readlane_b32 s9, v255, 1
	v_readlane_b32 s10, v255, 2
	v_readlane_b32 s11, v255, 3
	v_readlane_b32 s12, v255, 4
	v_readlane_b32 s13, v255, 5
	v_readlane_b32 s14, v255, 6
	v_readlane_b32 s15, v255, 7
	s_mov_b64 s[8:9], s[12:13]
	v_lshl_add_u64 v[52:53], v[130:131], 2, s[8:9]
	global_load_dwordx4 v[48:51], v[52:53], off
	ds_read_b32 v54, v133 offset:576
	v_lshlrev_b32_e32 v55, 12, v139
	s_mov_b64 s[10:11], s[14:15]
	v_lshl_add_u32 v56, v130, 2, v55
	s_waitcnt lgkmcnt(0)
	v_pk_mul_f32 v[46:47], v[46:47], v[54:55] op_sel_hi:[1,0]
	v_pk_mul_f32 v[44:45], v[44:45], v[54:55] op_sel_hi:[1,0]
	v_pk_mul_f32 v[38:39], v[38:39], v[54:55] op_sel_hi:[1,0]
	v_pk_mul_f32 v[36:37], v[36:37], v[54:55] op_sel_hi:[1,0]
	v_pk_mul_f32 v[42:43], v[42:43], v[54:55] op_sel_hi:[1,0]
	v_pk_mul_f32 v[40:41], v[40:41], v[54:55] op_sel_hi:[1,0]
	v_pk_mul_f32 v[34:35], v[34:35], v[54:55] op_sel_hi:[1,0]
	v_pk_mul_f32 v[32:33], v[32:33], v[54:55] op_sel_hi:[1,0]
	s_waitcnt vmcnt(0)
	v_pk_mul_f32 v[46:47], v[50:51], v[46:47]
	v_pk_mul_f32 v[44:45], v[48:49], v[44:45]
	global_store_dwordx4 v56, v[44:47], s[10:11] nt
	global_load_dwordx4 v[44:47], v[52:53], off offset:16
	v_lshl_add_u64 v[48:49], v[128:129], 2, s[8:9]
	s_waitcnt vmcnt(0)
	v_pk_mul_f32 v[38:39], v[38:39], v[46:47]
	v_pk_mul_f32 v[36:37], v[36:37], v[44:45]
	global_store_dwordx4 v56, v[36:39], s[10:11] offset:16 nt
	global_load_dwordx4 v[36:39], v[48:49], off
	v_lshl_add_u32 v44, v128, 2, v55
	s_waitcnt vmcnt(0)
	v_pk_mul_f32 v[38:39], v[42:43], v[38:39]
	v_pk_mul_f32 v[36:37], v[40:41], v[36:37]
	global_store_dwordx4 v44, v[36:39], s[10:11] nt
	global_load_dwordx4 v[36:39], v[48:49], off offset:16
	s_waitcnt vmcnt(0)
	v_pk_mul_f32 v[34:35], v[34:35], v[38:39]
	v_pk_mul_f32 v[32:33], v[32:33], v[36:37]
	global_store_dwordx4 v44, v[32:35], s[10:11] offset:16 nt
	s_or_b64 exec, exec, s[4:5]
	s_and_saveexec_b64 s[4:5], s[16:17]
	s_cbranch_execnz .LBB0_1012

.LBB0_1020:
	v_readlane_b32 s8, v255, 0
	v_readlane_b32 s9, v255, 1
	v_readlane_b32 s10, v255, 2
	v_readlane_b32 s11, v255, 3
	v_readlane_b32 s12, v255, 4
	v_readlane_b32 s13, v255, 5
	v_readlane_b32 s14, v255, 6
	v_readlane_b32 s15, v255, 7
	s_mov_b64 s[8:9], s[12:13]
	v_lshl_add_u64 v[20:21], v[130:131], 2, s[8:9]
	global_load_dwordx4 v[16:19], v[20:21], off
	ds_read_b32 v22, v133 offset:704
	v_lshlrev_b32_e32 v23, 12, v141
	s_mov_b64 s[10:11], s[14:15]
	v_lshl_add_u32 v24, v130, 2, v23
	s_waitcnt lgkmcnt(0)
	v_pk_mul_f32 v[14:15], v[14:15], v[22:23] op_sel_hi:[1,0]
	v_pk_mul_f32 v[12:13], v[12:13], v[22:23] op_sel_hi:[1,0]
	v_pk_mul_f32 v[6:7], v[6:7], v[22:23] op_sel_hi:[1,0]
	v_pk_mul_f32 v[4:5], v[4:5], v[22:23] op_sel_hi:[1,0]
	v_pk_mul_f32 v[10:11], v[10:11], v[22:23] op_sel_hi:[1,0]
	v_pk_mul_f32 v[8:9], v[8:9], v[22:23] op_sel_hi:[1,0]
	v_pk_mul_f32 v[2:3], v[2:3], v[22:23] op_sel_hi:[1,0]
	v_pk_mul_f32 v[0:1], v[0:1], v[22:23] op_sel_hi:[1,0]
	s_waitcnt vmcnt(0)
	v_pk_mul_f32 v[14:15], v[18:19], v[14:15]
	v_pk_mul_f32 v[12:13], v[16:17], v[12:13]
	global_store_dwordx4 v24, v[12:15], s[10:11] nt
	global_load_dwordx4 v[12:15], v[20:21], off offset:16
	v_lshl_add_u64 v[16:17], v[128:129], 2, s[8:9]
	s_waitcnt vmcnt(0)
	v_pk_mul_f32 v[6:7], v[6:7], v[14:15]
	v_pk_mul_f32 v[4:5], v[4:5], v[12:13]
	global_store_dwordx4 v24, v[4:7], s[10:11] offset:16 nt
	global_load_dwordx4 v[4:7], v[16:17], off
	v_lshl_add_u32 v12, v128, 2, v23
	s_waitcnt vmcnt(0)
	v_pk_mul_f32 v[6:7], v[10:11], v[6:7]
	v_pk_mul_f32 v[4:5], v[8:9], v[4:5]
	global_store_dwordx4 v12, v[4:7], s[10:11] nt
	global_load_dwordx4 v[4:7], v[16:17], off offset:16
	s_waitcnt vmcnt(0)
	v_pk_mul_f32 v[2:3], v[2:3], v[6:7]
	v_pk_mul_f32 v[0:1], v[0:1], v[4:5]
	global_store_dwordx4 v12, v[0:3], s[10:11] offset:16 nt

.LBB0_1050:
	s_andn2_b64 vcc, exec, s[4:5]
	s_cbranch_vccnz .LBB0_1052
	global_load_dwordx4 v[156:159], v[142:143], off
	s_waitcnt vmcnt(0)
	v_cvt_f32_f16_e32 v160, v157
	v_cvt_f32_f16_sdwa v161, v157 dst_sel:DWORD dst_unused:UNUSED_PAD src0_sel:WORD_1
	v_cvt_f32_f16_e32 v162, v156
	v_cvt_f32_f16_sdwa v163, v156 dst_sel:DWORD dst_unused:UNUSED_PAD src0_sel:WORD_1
	v_cvt_f32_f16_e32 v156, v159
	v_cvt_f32_f16_e32 v164, v158
	v_cvt_f32_f16_sdwa v165, v158 dst_sel:DWORD dst_unused:UNUSED_PAD src0_sel:WORD_1
	v_cvt_f32_f16_sdwa v157, v159 dst_sel:DWORD dst_unused:UNUSED_PAD src0_sel:WORD_1
	v_pk_mul_f32 v[162:163], v[124:125], v[162:163]
	v_pk_mul_f32 v[160:161], v[126:127], v[160:161]
	v_pk_mul_f32 v[164:165], v[120:121], v[164:165]
	v_pk_mul_f32 v[156:157], v[122:123], v[156:157]
	v_cvt_pk_f16_f32 v158, v164, v165
	v_cvt_pk_f16_f32 v159, v156, v157
	v_cvt_pk_f16_f32 v157, v160, v161
	v_cvt_pk_f16_f32 v156, v162, v163
	global_store_dwordx4 v[142:143], v[156:159], off nt

.LBB0_1053:
	s_andn2_b64 vcc, exec, s[4:5]
	s_cbranch_vccnz .LBB0_1055
	v_mul_f32_e32 v124, 0xbfb8aa3b, v124
	v_mul_f32_e32 v120, 0xbfb8aa3b, v120
	v_mul_f32_e32 v125, 0xbfb8aa3b, v125
	v_mul_f32_e32 v121, 0xbfb8aa3b, v121
	v_mul_f32_e32 v126, 0xbfb8aa3b, v126
	v_mul_f32_e32 v122, 0xbfb8aa3b, v122
	v_mul_f32_e32 v123, 0xbfb8aa3b, v123
	v_mul_f32_e32 v127, 0xbfb8aa3b, v127
	v_exp_f32_e32 v124, v124
	v_exp_f32_e32 v120, v120
	v_exp_f32_e32 v125, v125
	v_exp_f32_e32 v121, v121
	v_exp_f32_e32 v126, v126
	v_exp_f32_e32 v122, v122
	v_exp_f32_e32 v123, v123
	v_exp_f32_e32 v127, v127
	v_add_f32_e32 v124, 1.0, v124
	v_add_f32_e32 v120, 1.0, v120
	v_add_f32_e32 v125, 1.0, v125
	v_add_f32_e32 v121, 1.0, v121
	v_add_f32_e32 v126, 1.0, v126
	v_add_f32_e32 v122, 1.0, v122
	v_add_f32_e32 v123, 1.0, v123
	v_add_f32_e32 v127, 1.0, v127
	v_rcp_f32_e32 v124, v124
	v_rcp_f32_e32 v120, v120
	v_rcp_f32_e32 v121, v121
	v_rcp_f32_e32 v126, v126
	v_rcp_f32_e32 v122, v122
	v_rcp_f32_e32 v123, v123
	v_rcp_f32_e32 v127, v127
	v_rcp_f32_e32 v125, v125
	s_cmp_eq_u32 s63, 0
	v_cvt_pk_f16_f32 v123, v122, v123
	v_cvt_pk_f16_f32 v122, v120, v121
	v_cvt_pk_f16_f32 v121, v126, v127
	v_cvt_pk_f16_f32 v120, v124, v125
	s_cselect_b32 s5, s43, s45
	s_cselect_b32 s4, s42, s44
	global_store_dwordx4 v136, v[120:123], s[4:5] nt

.LBB0_1058:
	s_andn2_b64 vcc, exec, s[34:35]
	s_cbranch_vccnz .LBB0_1060
	global_load_dwordx4 v[120:123], v136, s[44:45] offset:256
	s_waitcnt vmcnt(0)
	v_cvt_f32_f16_e32 v124, v121
	v_cvt_f32_f16_sdwa v125, v121 dst_sel:DWORD dst_unused:UNUSED_PAD src0_sel:WORD_1
	v_cvt_f32_f16_e32 v126, v120
	v_cvt_f32_f16_sdwa v127, v120 dst_sel:DWORD dst_unused:UNUSED_PAD src0_sel:WORD_1
	v_cvt_f32_f16_e32 v120, v123
	v_cvt_f32_f16_e32 v142, v122
	v_cvt_f32_f16_sdwa v143, v122 dst_sel:DWORD dst_unused:UNUSED_PAD src0_sel:WORD_1
	v_cvt_f32_f16_sdwa v121, v123 dst_sel:DWORD dst_unused:UNUSED_PAD src0_sel:WORD_1
	v_pk_mul_f32 v[126:127], v[116:117], v[126:127]
	v_pk_mul_f32 v[124:125], v[118:119], v[124:125]
	v_pk_mul_f32 v[142:143], v[112:113], v[142:143]
	v_pk_mul_f32 v[120:121], v[114:115], v[120:121]
	v_cvt_pk_f16_f32 v122, v142, v143
	v_cvt_pk_f16_f32 v123, v120, v121
	v_cvt_pk_f16_f32 v121, v124, v125
	v_cvt_pk_f16_f32 v120, v126, v127
	global_store_dwordx4 v136, v[120:123], s[44:45] offset:256 nt

.LBB0_1064:
	s_andn2_b64 vcc, exec, s[34:35]
	s_cbranch_vccnz .LBB0_1066
	global_load_dwordx4 v[114:117], v[112:113], off
	s_waitcnt vmcnt(0)
	v_cvt_f32_f16_e32 v118, v115
	v_cvt_f32_f16_sdwa v119, v115 dst_sel:DWORD dst_unused:UNUSED_PAD src0_sel:WORD_1
	v_cvt_f32_f16_e32 v120, v114
	v_cvt_f32_f16_sdwa v121, v114 dst_sel:DWORD dst_unused:UNUSED_PAD src0_sel:WORD_1
	v_cvt_f32_f16_e32 v114, v117
	v_cvt_f32_f16_e32 v122, v116
	v_cvt_f32_f16_sdwa v123, v116 dst_sel:DWORD dst_unused:UNUSED_PAD src0_sel:WORD_1
	v_cvt_f32_f16_sdwa v115, v117 dst_sel:DWORD dst_unused:UNUSED_PAD src0_sel:WORD_1
	v_pk_mul_f32 v[120:121], v[108:109], v[120:121]
	v_pk_mul_f32 v[118:119], v[110:111], v[118:119]
	v_pk_mul_f32 v[122:123], v[104:105], v[122:123]
	v_pk_mul_f32 v[114:115], v[106:107], v[114:115]
	v_cvt_pk_f16_f32 v116, v122, v123
	v_cvt_pk_f16_f32 v117, v114, v115
	v_cvt_pk_f16_f32 v115, v118, v119
	v_cvt_pk_f16_f32 v114, v120, v121
	global_store_dwordx4 v[112:113], v[114:117], off nt

.LBB0_1070:
	s_andn2_b64 vcc, exec, s[34:35]
	s_cbranch_vccnz .LBB0_1072
	global_load_dwordx4 v[104:107], v136, s[44:45] offset:256
	s_waitcnt vmcnt(0)
	v_cvt_f32_f16_e32 v108, v105
	v_cvt_f32_f16_sdwa v109, v105 dst_sel:DWORD dst_unused:UNUSED_PAD src0_sel:WORD_1
	v_cvt_f32_f16_e32 v110, v104
	v_cvt_f32_f16_sdwa v111, v104 dst_sel:DWORD dst_unused:UNUSED_PAD src0_sel:WORD_1
	v_cvt_f32_f16_e32 v104, v107
	v_cvt_f32_f16_e32 v112, v106
	v_cvt_f32_f16_sdwa v113, v106 dst_sel:DWORD dst_unused:UNUSED_PAD src0_sel:WORD_1
	v_cvt_f32_f16_sdwa v105, v107 dst_sel:DWORD dst_unused:UNUSED_PAD src0_sel:WORD_1
	v_pk_mul_f32 v[110:111], v[100:101], v[110:111]
	v_pk_mul_f32 v[108:109], v[102:103], v[108:109]
	v_pk_mul_f32 v[112:113], v[96:97], v[112:113]
	v_pk_mul_f32 v[104:105], v[98:99], v[104:105]
	v_cvt_pk_f16_f32 v106, v112, v113
	v_cvt_pk_f16_f32 v107, v104, v105
	v_cvt_pk_f16_f32 v105, v108, v109
	v_cvt_pk_f16_f32 v104, v110, v111
	global_store_dwordx4 v136, v[104:107], s[44:45] offset:256 nt

.LBB0_1076:
	s_andn2_b64 vcc, exec, s[34:35]
	s_cbranch_vccnz .LBB0_1078
	global_load_dwordx4 v[98:101], v[96:97], off
	s_waitcnt vmcnt(0)
	v_cvt_f32_f16_e32 v102, v99
	v_cvt_f32_f16_sdwa v103, v99 dst_sel:DWORD dst_unused:UNUSED_PAD src0_sel:WORD_1
	v_cvt_f32_f16_e32 v104, v98
	v_cvt_f32_f16_sdwa v105, v98 dst_sel:DWORD dst_unused:UNUSED_PAD src0_sel:WORD_1
	v_cvt_f32_f16_e32 v98, v101
	v_cvt_f32_f16_e32 v106, v100
	v_cvt_f32_f16_sdwa v107, v100 dst_sel:DWORD dst_unused:UNUSED_PAD src0_sel:WORD_1
	v_cvt_f32_f16_sdwa v99, v101 dst_sel:DWORD dst_unused:UNUSED_PAD src0_sel:WORD_1
	v_pk_mul_f32 v[104:105], v[92:93], v[104:105]
	v_pk_mul_f32 v[102:103], v[94:95], v[102:103]
	v_pk_mul_f32 v[106:107], v[88:89], v[106:107]
	v_pk_mul_f32 v[98:99], v[90:91], v[98:99]
	v_cvt_pk_f16_f32 v100, v106, v107
	v_cvt_pk_f16_f32 v101, v98, v99
	v_cvt_pk_f16_f32 v99, v102, v103
	v_cvt_pk_f16_f32 v98, v104, v105
	global_store_dwordx4 v[96:97], v[98:101], off nt

.LBB0_1082:
	s_andn2_b64 vcc, exec, s[34:35]
	s_cbranch_vccnz .LBB0_1084
	global_load_dwordx4 v[88:91], v136, s[44:45] offset:256
	s_waitcnt vmcnt(0)
	v_cvt_f32_f16_e32 v92, v89
	v_cvt_f32_f16_sdwa v93, v89 dst_sel:DWORD dst_unused:UNUSED_PAD src0_sel:WORD_1
	v_cvt_f32_f16_e32 v94, v88
	v_cvt_f32_f16_sdwa v95, v88 dst_sel:DWORD dst_unused:UNUSED_PAD src0_sel:WORD_1
	v_cvt_f32_f16_e32 v88, v91
	v_cvt_f32_f16_e32 v96, v90
	v_cvt_f32_f16_sdwa v97, v90 dst_sel:DWORD dst_unused:UNUSED_PAD src0_sel:WORD_1
	v_cvt_f32_f16_sdwa v89, v91 dst_sel:DWORD dst_unused:UNUSED_PAD src0_sel:WORD_1
	v_pk_mul_f32 v[94:95], v[84:85], v[94:95]
	v_pk_mul_f32 v[92:93], v[86:87], v[92:93]
	v_pk_mul_f32 v[96:97], v[80:81], v[96:97]
	v_pk_mul_f32 v[88:89], v[82:83], v[88:89]
	v_cvt_pk_f16_f32 v90, v96, v97
	v_cvt_pk_f16_f32 v91, v88, v89
	v_cvt_pk_f16_f32 v89, v92, v93
	v_cvt_pk_f16_f32 v88, v94, v95
	global_store_dwordx4 v136, v[88:91], s[44:45] offset:256 nt

.LBB0_1088:
	s_andn2_b64 vcc, exec, s[34:35]
	s_cbranch_vccnz .LBB0_1090
	global_load_dwordx4 v[82:85], v[80:81], off
	s_waitcnt vmcnt(0)
	v_cvt_f32_f16_e32 v86, v83
	v_cvt_f32_f16_sdwa v87, v83 dst_sel:DWORD dst_unused:UNUSED_PAD src0_sel:WORD_1
	v_cvt_f32_f16_e32 v88, v82
	v_cvt_f32_f16_sdwa v89, v82 dst_sel:DWORD dst_unused:UNUSED_PAD src0_sel:WORD_1
	v_cvt_f32_f16_e32 v82, v85
	v_cvt_f32_f16_e32 v90, v84
	v_cvt_f32_f16_sdwa v91, v84 dst_sel:DWORD dst_unused:UNUSED_PAD src0_sel:WORD_1
	v_cvt_f32_f16_sdwa v83, v85 dst_sel:DWORD dst_unused:UNUSED_PAD src0_sel:WORD_1
	v_pk_mul_f32 v[88:89], v[76:77], v[88:89]
	v_pk_mul_f32 v[86:87], v[78:79], v[86:87]
	v_pk_mul_f32 v[90:91], v[72:73], v[90:91]
	v_pk_mul_f32 v[82:83], v[74:75], v[82:83]
	v_cvt_pk_f16_f32 v84, v90, v91
	v_cvt_pk_f16_f32 v85, v82, v83
	v_cvt_pk_f16_f32 v83, v86, v87
	v_cvt_pk_f16_f32 v82, v88, v89
	global_store_dwordx4 v[80:81], v[82:85], off nt

.LBB0_1094:
	s_andn2_b64 vcc, exec, s[34:35]
	s_cbranch_vccnz .LBB0_1096
	global_load_dwordx4 v[72:75], v136, s[44:45] offset:256
	s_waitcnt vmcnt(0)
	v_cvt_f32_f16_e32 v76, v73
	v_cvt_f32_f16_sdwa v77, v73 dst_sel:DWORD dst_unused:UNUSED_PAD src0_sel:WORD_1
	v_cvt_f32_f16_e32 v78, v72
	v_cvt_f32_f16_sdwa v79, v72 dst_sel:DWORD dst_unused:UNUSED_PAD src0_sel:WORD_1
	v_cvt_f32_f16_e32 v72, v75
	v_cvt_f32_f16_e32 v80, v74
	v_cvt_f32_f16_sdwa v81, v74 dst_sel:DWORD dst_unused:UNUSED_PAD src0_sel:WORD_1
	v_cvt_f32_f16_sdwa v73, v75 dst_sel:DWORD dst_unused:UNUSED_PAD src0_sel:WORD_1
	v_pk_mul_f32 v[78:79], v[68:69], v[78:79]
	v_pk_mul_f32 v[76:77], v[70:71], v[76:77]
	v_pk_mul_f32 v[80:81], v[64:65], v[80:81]
	v_pk_mul_f32 v[72:73], v[66:67], v[72:73]
	v_cvt_pk_f16_f32 v74, v80, v81
	v_cvt_pk_f16_f32 v75, v72, v73
	v_cvt_pk_f16_f32 v73, v76, v77
	v_cvt_pk_f16_f32 v72, v78, v79
	global_store_dwordx4 v136, v[72:75], s[44:45] offset:256 nt

.LBB0_1100:
	s_andn2_b64 vcc, exec, s[34:35]
	s_cbranch_vccnz .LBB0_1102
	global_load_dwordx4 v[66:69], v[64:65], off
	s_waitcnt vmcnt(0)
	v_cvt_f32_f16_e32 v70, v67
	v_cvt_f32_f16_sdwa v71, v67 dst_sel:DWORD dst_unused:UNUSED_PAD src0_sel:WORD_1
	v_cvt_f32_f16_e32 v72, v66
	v_cvt_f32_f16_sdwa v73, v66 dst_sel:DWORD dst_unused:UNUSED_PAD src0_sel:WORD_1
	v_cvt_f32_f16_e32 v66, v69
	v_cvt_f32_f16_e32 v74, v68
	v_cvt_f32_f16_sdwa v75, v68 dst_sel:DWORD dst_unused:UNUSED_PAD src0_sel:WORD_1
	v_cvt_f32_f16_sdwa v67, v69 dst_sel:DWORD dst_unused:UNUSED_PAD src0_sel:WORD_1
	v_pk_mul_f32 v[72:73], v[60:61], v[72:73]
	v_pk_mul_f32 v[70:71], v[62:63], v[70:71]
	v_pk_mul_f32 v[74:75], v[56:57], v[74:75]
	v_pk_mul_f32 v[66:67], v[58:59], v[66:67]
	v_cvt_pk_f16_f32 v68, v74, v75
	v_cvt_pk_f16_f32 v69, v66, v67
	v_cvt_pk_f16_f32 v67, v70, v71
	v_cvt_pk_f16_f32 v66, v72, v73
	global_store_dwordx4 v[64:65], v[66:69], off nt

.LBB0_1106:
	s_andn2_b64 vcc, exec, s[34:35]
	s_cbranch_vccnz .LBB0_1108
	global_load_dwordx4 v[56:59], v136, s[44:45] offset:256
	s_waitcnt vmcnt(0)
	v_cvt_f32_f16_e32 v60, v57
	v_cvt_f32_f16_sdwa v61, v57 dst_sel:DWORD dst_unused:UNUSED_PAD src0_sel:WORD_1
	v_cvt_f32_f16_e32 v62, v56
	v_cvt_f32_f16_sdwa v63, v56 dst_sel:DWORD dst_unused:UNUSED_PAD src0_sel:WORD_1
	v_cvt_f32_f16_e32 v56, v59
	v_cvt_f32_f16_e32 v64, v58
	v_cvt_f32_f16_sdwa v65, v58 dst_sel:DWORD dst_unused:UNUSED_PAD src0_sel:WORD_1
	v_cvt_f32_f16_sdwa v57, v59 dst_sel:DWORD dst_unused:UNUSED_PAD src0_sel:WORD_1
	v_pk_mul_f32 v[62:63], v[52:53], v[62:63]
	v_pk_mul_f32 v[60:61], v[54:55], v[60:61]
	v_pk_mul_f32 v[64:65], v[48:49], v[64:65]
	v_pk_mul_f32 v[56:57], v[50:51], v[56:57]
	v_cvt_pk_f16_f32 v58, v64, v65
	v_cvt_pk_f16_f32 v59, v56, v57
	v_cvt_pk_f16_f32 v57, v60, v61
	v_cvt_pk_f16_f32 v56, v62, v63
	global_store_dwordx4 v136, v[56:59], s[44:45] offset:256 nt

.LBB0_1112:
	s_andn2_b64 vcc, exec, s[34:35]
	s_cbranch_vccnz .LBB0_1114
	global_load_dwordx4 v[50:53], v[48:49], off
	s_waitcnt vmcnt(0)
	v_cvt_f32_f16_e32 v54, v51
	v_cvt_f32_f16_sdwa v55, v51 dst_sel:DWORD dst_unused:UNUSED_PAD src0_sel:WORD_1
	v_cvt_f32_f16_e32 v56, v50
	v_cvt_f32_f16_sdwa v57, v50 dst_sel:DWORD dst_unused:UNUSED_PAD src0_sel:WORD_1
	v_cvt_f32_f16_e32 v50, v53
	v_cvt_f32_f16_e32 v58, v52
	v_cvt_f32_f16_sdwa v59, v52 dst_sel:DWORD dst_unused:UNUSED_PAD src0_sel:WORD_1
	v_cvt_f32_f16_sdwa v51, v53 dst_sel:DWORD dst_unused:UNUSED_PAD src0_sel:WORD_1
	v_pk_mul_f32 v[56:57], v[44:45], v[56:57]
	v_pk_mul_f32 v[54:55], v[46:47], v[54:55]
	v_pk_mul_f32 v[58:59], v[40:41], v[58:59]
	v_pk_mul_f32 v[50:51], v[42:43], v[50:51]
	v_cvt_pk_f16_f32 v52, v58, v59
	v_cvt_pk_f16_f32 v53, v50, v51
	v_cvt_pk_f16_f32 v51, v54, v55
	v_cvt_pk_f16_f32 v50, v56, v57
	global_store_dwordx4 v[48:49], v[50:53], off nt

.LBB0_1118:
	s_andn2_b64 vcc, exec, s[34:35]
	s_cbranch_vccnz .LBB0_1120
	global_load_dwordx4 v[40:43], v136, s[44:45] offset:256
	s_waitcnt vmcnt(0)
	v_cvt_f32_f16_e32 v44, v41
	v_cvt_f32_f16_sdwa v45, v41 dst_sel:DWORD dst_unused:UNUSED_PAD src0_sel:WORD_1
	v_cvt_f32_f16_e32 v46, v40
	v_cvt_f32_f16_sdwa v47, v40 dst_sel:DWORD dst_unused:UNUSED_PAD src0_sel:WORD_1
	v_cvt_f32_f16_e32 v40, v43
	v_cvt_f32_f16_e32 v48, v42
	v_cvt_f32_f16_sdwa v49, v42 dst_sel:DWORD dst_unused:UNUSED_PAD src0_sel:WORD_1
	v_cvt_f32_f16_sdwa v41, v43 dst_sel:DWORD dst_unused:UNUSED_PAD src0_sel:WORD_1
	v_pk_mul_f32 v[46:47], v[36:37], v[46:47]
	v_pk_mul_f32 v[44:45], v[38:39], v[44:45]
	v_pk_mul_f32 v[48:49], v[32:33], v[48:49]
	v_pk_mul_f32 v[40:41], v[34:35], v[40:41]
	v_cvt_pk_f16_f32 v42, v48, v49
	v_cvt_pk_f16_f32 v43, v40, v41
	v_cvt_pk_f16_f32 v41, v44, v45
	v_cvt_pk_f16_f32 v40, v46, v47
	global_store_dwordx4 v136, v[40:43], s[44:45] offset:256 nt

.LBB0_1124:
	s_andn2_b64 vcc, exec, s[34:35]
	s_cbranch_vccnz .LBB0_1126
	global_load_dwordx4 v[34:37], v[32:33], off
	s_waitcnt vmcnt(0)
	v_cvt_f32_f16_e32 v38, v35
	v_cvt_f32_f16_sdwa v39, v35 dst_sel:DWORD dst_unused:UNUSED_PAD src0_sel:WORD_1
	v_cvt_f32_f16_e32 v40, v34
	v_cvt_f32_f16_sdwa v41, v34 dst_sel:DWORD dst_unused:UNUSED_PAD src0_sel:WORD_1
	v_cvt_f32_f16_e32 v34, v37
	v_cvt_f32_f16_e32 v42, v36
	v_cvt_f32_f16_sdwa v43, v36 dst_sel:DWORD dst_unused:UNUSED_PAD src0_sel:WORD_1
	v_cvt_f32_f16_sdwa v35, v37 dst_sel:DWORD dst_unused:UNUSED_PAD src0_sel:WORD_1
	v_pk_mul_f32 v[40:41], v[28:29], v[40:41]
	v_pk_mul_f32 v[38:39], v[30:31], v[38:39]
	v_pk_mul_f32 v[42:43], v[24:25], v[42:43]
	v_pk_mul_f32 v[34:35], v[26:27], v[34:35]
	v_cvt_pk_f16_f32 v36, v42, v43
	v_cvt_pk_f16_f32 v37, v34, v35
	v_cvt_pk_f16_f32 v35, v38, v39
	v_cvt_pk_f16_f32 v34, v40, v41
	global_store_dwordx4 v[32:33], v[34:37], off nt

.LBB0_1130:
	s_andn2_b64 vcc, exec, s[34:35]
	s_cbranch_vccnz .LBB0_1132
	global_load_dwordx4 v[24:27], v136, s[44:45] offset:256
	s_waitcnt vmcnt(0)
	v_cvt_f32_f16_e32 v28, v25
	v_cvt_f32_f16_sdwa v29, v25 dst_sel:DWORD dst_unused:UNUSED_PAD src0_sel:WORD_1
	v_cvt_f32_f16_e32 v30, v24
	v_cvt_f32_f16_sdwa v31, v24 dst_sel:DWORD dst_unused:UNUSED_PAD src0_sel:WORD_1
	v_cvt_f32_f16_e32 v24, v27
	v_cvt_f32_f16_e32 v32, v26
	v_cvt_f32_f16_sdwa v33, v26 dst_sel:DWORD dst_unused:UNUSED_PAD src0_sel:WORD_1
	v_cvt_f32_f16_sdwa v25, v27 dst_sel:DWORD dst_unused:UNUSED_PAD src0_sel:WORD_1
	v_pk_mul_f32 v[30:31], v[20:21], v[30:31]
	v_pk_mul_f32 v[28:29], v[22:23], v[28:29]
	v_pk_mul_f32 v[32:33], v[16:17], v[32:33]
	v_pk_mul_f32 v[24:25], v[18:19], v[24:25]
	v_cvt_pk_f16_f32 v26, v32, v33
	v_cvt_pk_f16_f32 v27, v24, v25
	v_cvt_pk_f16_f32 v25, v28, v29
	v_cvt_pk_f16_f32 v24, v30, v31
	global_store_dwordx4 v136, v[24:27], s[44:45] offset:256 nt

.LBB0_1136:
	s_andn2_b64 vcc, exec, s[34:35]
	s_cbranch_vccnz .LBB0_1138
	global_load_dwordx4 v[18:21], v[16:17], off
	s_waitcnt vmcnt(0)
	v_cvt_f32_f16_e32 v22, v19
	v_cvt_f32_f16_sdwa v23, v19 dst_sel:DWORD dst_unused:UNUSED_PAD src0_sel:WORD_1
	v_cvt_f32_f16_e32 v24, v18
	v_cvt_f32_f16_sdwa v25, v18 dst_sel:DWORD dst_unused:UNUSED_PAD src0_sel:WORD_1
	v_cvt_f32_f16_e32 v18, v21
	v_cvt_f32_f16_e32 v26, v20
	v_cvt_f32_f16_sdwa v27, v20 dst_sel:DWORD dst_unused:UNUSED_PAD src0_sel:WORD_1
	v_cvt_f32_f16_sdwa v19, v21 dst_sel:DWORD dst_unused:UNUSED_PAD src0_sel:WORD_1
	v_pk_mul_f32 v[24:25], v[12:13], v[24:25]
	v_pk_mul_f32 v[22:23], v[14:15], v[22:23]
	v_pk_mul_f32 v[26:27], v[8:9], v[26:27]
	v_pk_mul_f32 v[18:19], v[10:11], v[18:19]
	v_cvt_pk_f16_f32 v20, v26, v27
	v_cvt_pk_f16_f32 v21, v18, v19
	v_cvt_pk_f16_f32 v19, v22, v23
	v_cvt_pk_f16_f32 v18, v24, v25
	global_store_dwordx4 v[16:17], v[18:21], off nt

.LBB0_1142:
	s_andn2_b64 vcc, exec, s[4:5]
	s_cbranch_vccnz .LBB0_1144
	global_load_dwordx4 v[8:11], v136, s[44:45] offset:256
	s_waitcnt vmcnt(0)
	v_cvt_f32_f16_e32 v12, v9
	v_cvt_f32_f16_sdwa v13, v9 dst_sel:DWORD dst_unused:UNUSED_PAD src0_sel:WORD_1
	v_cvt_f32_f16_e32 v14, v8
	v_cvt_f32_f16_sdwa v15, v8 dst_sel:DWORD dst_unused:UNUSED_PAD src0_sel:WORD_1
	v_cvt_f32_f16_e32 v8, v11
	v_cvt_f32_f16_e32 v16, v10
	v_cvt_f32_f16_sdwa v17, v10 dst_sel:DWORD dst_unused:UNUSED_PAD src0_sel:WORD_1
	v_cvt_f32_f16_sdwa v9, v11 dst_sel:DWORD dst_unused:UNUSED_PAD src0_sel:WORD_1
	v_pk_mul_f32 v[14:15], v[4:5], v[14:15]
	v_pk_mul_f32 v[12:13], v[6:7], v[12:13]
	v_pk_mul_f32 v[16:17], v[0:1], v[16:17]
	v_pk_mul_f32 v[8:9], v[2:3], v[8:9]
	v_cvt_pk_f16_f32 v10, v16, v17
	v_cvt_pk_f16_f32 v11, v8, v9
	v_cvt_pk_f16_f32 v9, v12, v13
	v_cvt_pk_f16_f32 v8, v14, v15
	global_store_dwordx4 v136, v[8:11], s[44:45] offset:256 nt

.LBB0_1147:
	v_mul_f32_e32 v116, 0xbfb8aa3b, v116
	v_mul_f32_e32 v112, 0xbfb8aa3b, v112
	v_mul_f32_e32 v117, 0xbfb8aa3b, v117
	v_mul_f32_e32 v113, 0xbfb8aa3b, v113
	v_mul_f32_e32 v118, 0xbfb8aa3b, v118
	v_mul_f32_e32 v114, 0xbfb8aa3b, v114
	v_mul_f32_e32 v115, 0xbfb8aa3b, v115
	v_mul_f32_e32 v119, 0xbfb8aa3b, v119
	v_exp_f32_e32 v116, v116
	v_exp_f32_e32 v112, v112
	v_exp_f32_e32 v117, v117
	v_exp_f32_e32 v113, v113
	v_exp_f32_e32 v118, v118
	v_exp_f32_e32 v114, v114
	v_exp_f32_e32 v115, v115
	v_exp_f32_e32 v119, v119
	v_add_f32_e32 v116, 1.0, v116
	v_add_f32_e32 v112, 1.0, v112
	v_add_f32_e32 v117, 1.0, v117
	v_add_f32_e32 v113, 1.0, v113
	v_add_f32_e32 v118, 1.0, v118
	v_add_f32_e32 v114, 1.0, v114
	v_add_f32_e32 v115, 1.0, v115
	v_add_f32_e32 v119, 1.0, v119
	v_rcp_f32_e32 v116, v116
	v_rcp_f32_e32 v112, v112
	v_rcp_f32_e32 v113, v113
	v_rcp_f32_e32 v118, v118
	v_rcp_f32_e32 v114, v114
	v_rcp_f32_e32 v115, v115
	v_rcp_f32_e32 v119, v119
	v_rcp_f32_e32 v117, v117
	s_cmp_eq_u32 s63, 0
	v_cvt_pk_f16_f32 v115, v114, v115
	v_cvt_pk_f16_f32 v114, v112, v113
	v_cvt_pk_f16_f32 v113, v118, v119
	v_cvt_pk_f16_f32 v112, v116, v117
	s_cselect_b32 s35, s43, s45
	s_cselect_b32 s34, s42, s44
	global_store_dwordx4 v136, v[112:115], s[34:35] offset:256 nt
	v_add_u32_e32 v136, s28, v146
	s_and_b64 vcc, exec, s[4:5]
	s_mov_b64 s[34:35], -1
	s_cbranch_vccz .LBB0_1062

.LBB0_1149:
	v_mul_f32_e32 v108, 0xbfb8aa3b, v108
	v_mul_f32_e32 v104, 0xbfb8aa3b, v104
	v_mul_f32_e32 v109, 0xbfb8aa3b, v109
	v_mul_f32_e32 v105, 0xbfb8aa3b, v105
	v_mul_f32_e32 v110, 0xbfb8aa3b, v110
	v_mul_f32_e32 v106, 0xbfb8aa3b, v106
	v_mul_f32_e32 v107, 0xbfb8aa3b, v107
	v_mul_f32_e32 v111, 0xbfb8aa3b, v111
	v_exp_f32_e32 v108, v108
	v_exp_f32_e32 v104, v104
	v_exp_f32_e32 v109, v109
	v_exp_f32_e32 v105, v105
	v_exp_f32_e32 v110, v110
	v_exp_f32_e32 v106, v106
	v_exp_f32_e32 v107, v107
	v_exp_f32_e32 v111, v111
	v_add_f32_e32 v108, 1.0, v108
	v_add_f32_e32 v104, 1.0, v104
	v_add_f32_e32 v109, 1.0, v109
	v_add_f32_e32 v105, 1.0, v105
	v_add_f32_e32 v110, 1.0, v110
	v_add_f32_e32 v106, 1.0, v106
	v_add_f32_e32 v107, 1.0, v107
	v_add_f32_e32 v111, 1.0, v111
	v_rcp_f32_e32 v108, v108
	v_rcp_f32_e32 v104, v104
	v_rcp_f32_e32 v105, v105
	v_rcp_f32_e32 v110, v110
	v_rcp_f32_e32 v106, v106
	v_rcp_f32_e32 v107, v107
	v_rcp_f32_e32 v111, v111
	v_rcp_f32_e32 v109, v109
	s_cmp_eq_u32 s63, 0
	v_cvt_pk_f16_f32 v107, v106, v107
	v_cvt_pk_f16_f32 v106, v104, v105
	v_cvt_pk_f16_f32 v105, v110, v111
	v_cvt_pk_f16_f32 v104, v108, v109
	s_cselect_b32 s35, s43, s45
	s_cselect_b32 s34, s42, s44
	global_store_dwordx4 v136, v[104:107], s[34:35] nt
	s_and_b64 vcc, exec, s[4:5]
	s_mov_b64 s[34:35], -1
	s_cbranch_vccz .LBB0_1068

.LBB0_1151:
	v_mul_f32_e32 v100, 0xbfb8aa3b, v100
	v_mul_f32_e32 v96, 0xbfb8aa3b, v96
	v_mul_f32_e32 v101, 0xbfb8aa3b, v101
	v_mul_f32_e32 v97, 0xbfb8aa3b, v97
	v_mul_f32_e32 v102, 0xbfb8aa3b, v102
	v_mul_f32_e32 v98, 0xbfb8aa3b, v98
	v_mul_f32_e32 v99, 0xbfb8aa3b, v99
	v_mul_f32_e32 v103, 0xbfb8aa3b, v103
	v_exp_f32_e32 v100, v100
	v_exp_f32_e32 v96, v96
	v_exp_f32_e32 v101, v101
	v_exp_f32_e32 v97, v97
	v_exp_f32_e32 v102, v102
	v_exp_f32_e32 v98, v98
	v_exp_f32_e32 v99, v99
	v_exp_f32_e32 v103, v103
	v_add_f32_e32 v100, 1.0, v100
	v_add_f32_e32 v96, 1.0, v96
	v_add_f32_e32 v101, 1.0, v101
	v_add_f32_e32 v97, 1.0, v97
	v_add_f32_e32 v102, 1.0, v102
	v_add_f32_e32 v98, 1.0, v98
	v_add_f32_e32 v99, 1.0, v99
	v_add_f32_e32 v103, 1.0, v103
	v_rcp_f32_e32 v100, v100
	v_rcp_f32_e32 v96, v96
	v_rcp_f32_e32 v97, v97
	v_rcp_f32_e32 v102, v102
	v_rcp_f32_e32 v98, v98
	v_rcp_f32_e32 v99, v99
	v_rcp_f32_e32 v103, v103
	v_rcp_f32_e32 v101, v101
	s_cmp_eq_u32 s63, 0
	v_cvt_pk_f16_f32 v99, v98, v99
	v_cvt_pk_f16_f32 v98, v96, v97
	v_cvt_pk_f16_f32 v97, v102, v103
	v_cvt_pk_f16_f32 v96, v100, v101
	s_cselect_b32 s35, s43, s45
	s_cselect_b32 s34, s42, s44
	global_store_dwordx4 v136, v[96:99], s[34:35] offset:256 nt
	v_add_u32_e32 v136, s28, v147
	s_and_b64 vcc, exec, s[4:5]
	s_mov_b64 s[34:35], -1
	s_cbranch_vccz .LBB0_1074

.LBB0_1153:
	v_mul_f32_e32 v92, 0xbfb8aa3b, v92
	v_mul_f32_e32 v88, 0xbfb8aa3b, v88
	v_mul_f32_e32 v93, 0xbfb8aa3b, v93
	v_mul_f32_e32 v89, 0xbfb8aa3b, v89
	v_mul_f32_e32 v94, 0xbfb8aa3b, v94
	v_mul_f32_e32 v90, 0xbfb8aa3b, v90
	v_mul_f32_e32 v91, 0xbfb8aa3b, v91
	v_mul_f32_e32 v95, 0xbfb8aa3b, v95
	v_exp_f32_e32 v92, v92
	v_exp_f32_e32 v88, v88
	v_exp_f32_e32 v93, v93
	v_exp_f32_e32 v89, v89
	v_exp_f32_e32 v94, v94
	v_exp_f32_e32 v90, v90
	v_exp_f32_e32 v91, v91
	v_exp_f32_e32 v95, v95
	v_add_f32_e32 v92, 1.0, v92
	v_add_f32_e32 v88, 1.0, v88
	v_add_f32_e32 v93, 1.0, v93
	v_add_f32_e32 v89, 1.0, v89
	v_add_f32_e32 v94, 1.0, v94
	v_add_f32_e32 v90, 1.0, v90
	v_add_f32_e32 v91, 1.0, v91
	v_add_f32_e32 v95, 1.0, v95
	v_rcp_f32_e32 v92, v92
	v_rcp_f32_e32 v88, v88
	v_rcp_f32_e32 v89, v89
	v_rcp_f32_e32 v94, v94
	v_rcp_f32_e32 v90, v90
	v_rcp_f32_e32 v91, v91
	v_rcp_f32_e32 v95, v95
	v_rcp_f32_e32 v93, v93
	s_cmp_eq_u32 s63, 0
	v_cvt_pk_f16_f32 v91, v90, v91
	v_cvt_pk_f16_f32 v90, v88, v89
	v_cvt_pk_f16_f32 v89, v94, v95
	v_cvt_pk_f16_f32 v88, v92, v93
	s_cselect_b32 s35, s43, s45
	s_cselect_b32 s34, s42, s44
	global_store_dwordx4 v136, v[88:91], s[34:35] nt
	s_and_b64 vcc, exec, s[4:5]
	s_mov_b64 s[34:35], -1
	s_cbranch_vccz .LBB0_1080

.LBB0_1155:
	v_mul_f32_e32 v84, 0xbfb8aa3b, v84
	v_mul_f32_e32 v80, 0xbfb8aa3b, v80
	v_mul_f32_e32 v85, 0xbfb8aa3b, v85
	v_mul_f32_e32 v81, 0xbfb8aa3b, v81
	v_mul_f32_e32 v86, 0xbfb8aa3b, v86
	v_mul_f32_e32 v82, 0xbfb8aa3b, v82
	v_mul_f32_e32 v83, 0xbfb8aa3b, v83
	v_mul_f32_e32 v87, 0xbfb8aa3b, v87
	v_exp_f32_e32 v84, v84
	v_exp_f32_e32 v80, v80
	v_exp_f32_e32 v85, v85
	v_exp_f32_e32 v81, v81
	v_exp_f32_e32 v86, v86
	v_exp_f32_e32 v82, v82
	v_exp_f32_e32 v83, v83
	v_exp_f32_e32 v87, v87
	v_add_f32_e32 v84, 1.0, v84
	v_add_f32_e32 v80, 1.0, v80
	v_add_f32_e32 v85, 1.0, v85
	v_add_f32_e32 v81, 1.0, v81
	v_add_f32_e32 v86, 1.0, v86
	v_add_f32_e32 v82, 1.0, v82
	v_add_f32_e32 v83, 1.0, v83
	v_add_f32_e32 v87, 1.0, v87
	v_rcp_f32_e32 v84, v84
	v_rcp_f32_e32 v80, v80
	v_rcp_f32_e32 v81, v81
	v_rcp_f32_e32 v86, v86
	v_rcp_f32_e32 v82, v82
	v_rcp_f32_e32 v83, v83
	v_rcp_f32_e32 v87, v87
	v_rcp_f32_e32 v85, v85
	s_cmp_eq_u32 s63, 0
	v_cvt_pk_f16_f32 v83, v82, v83
	v_cvt_pk_f16_f32 v82, v80, v81
	v_cvt_pk_f16_f32 v81, v86, v87
	v_cvt_pk_f16_f32 v80, v84, v85
	s_cselect_b32 s35, s43, s45
	s_cselect_b32 s34, s42, s44
	global_store_dwordx4 v136, v[80:83], s[34:35] offset:256 nt
	v_add_u32_e32 v136, s28, v148
	s_and_b64 vcc, exec, s[4:5]
	s_mov_b64 s[34:35], -1
	s_cbranch_vccz .LBB0_1086

.LBB0_1157:
	v_mul_f32_e32 v76, 0xbfb8aa3b, v76
	v_mul_f32_e32 v72, 0xbfb8aa3b, v72
	v_mul_f32_e32 v77, 0xbfb8aa3b, v77
	v_mul_f32_e32 v73, 0xbfb8aa3b, v73
	v_mul_f32_e32 v78, 0xbfb8aa3b, v78
	v_mul_f32_e32 v74, 0xbfb8aa3b, v74
	v_mul_f32_e32 v75, 0xbfb8aa3b, v75
	v_mul_f32_e32 v79, 0xbfb8aa3b, v79
	v_exp_f32_e32 v76, v76
	v_exp_f32_e32 v72, v72
	v_exp_f32_e32 v77, v77
	v_exp_f32_e32 v73, v73
	v_exp_f32_e32 v78, v78
	v_exp_f32_e32 v74, v74
	v_exp_f32_e32 v75, v75
	v_exp_f32_e32 v79, v79
	v_add_f32_e32 v76, 1.0, v76
	v_add_f32_e32 v72, 1.0, v72
	v_add_f32_e32 v77, 1.0, v77
	v_add_f32_e32 v73, 1.0, v73
	v_add_f32_e32 v78, 1.0, v78
	v_add_f32_e32 v74, 1.0, v74
	v_add_f32_e32 v75, 1.0, v75
	v_add_f32_e32 v79, 1.0, v79
	v_rcp_f32_e32 v76, v76
	v_rcp_f32_e32 v72, v72
	v_rcp_f32_e32 v73, v73
	v_rcp_f32_e32 v78, v78
	v_rcp_f32_e32 v74, v74
	v_rcp_f32_e32 v75, v75
	v_rcp_f32_e32 v79, v79
	v_rcp_f32_e32 v77, v77
	s_cmp_eq_u32 s63, 0
	v_cvt_pk_f16_f32 v75, v74, v75
	v_cvt_pk_f16_f32 v74, v72, v73
	v_cvt_pk_f16_f32 v73, v78, v79
	v_cvt_pk_f16_f32 v72, v76, v77
	s_cselect_b32 s35, s43, s45
	s_cselect_b32 s34, s42, s44
	global_store_dwordx4 v136, v[72:75], s[34:35] nt
	s_and_b64 vcc, exec, s[4:5]
	s_mov_b64 s[34:35], -1
	s_cbranch_vccz .LBB0_1092

.LBB0_1159:
	v_mul_f32_e32 v68, 0xbfb8aa3b, v68
	v_mul_f32_e32 v64, 0xbfb8aa3b, v64
	v_mul_f32_e32 v69, 0xbfb8aa3b, v69
	v_mul_f32_e32 v65, 0xbfb8aa3b, v65
	v_mul_f32_e32 v70, 0xbfb8aa3b, v70
	v_mul_f32_e32 v66, 0xbfb8aa3b, v66
	v_mul_f32_e32 v67, 0xbfb8aa3b, v67
	v_mul_f32_e32 v71, 0xbfb8aa3b, v71
	v_exp_f32_e32 v68, v68
	v_exp_f32_e32 v64, v64
	v_exp_f32_e32 v69, v69
	v_exp_f32_e32 v65, v65
	v_exp_f32_e32 v70, v70
	v_exp_f32_e32 v66, v66
	v_exp_f32_e32 v67, v67
	v_exp_f32_e32 v71, v71
	v_add_f32_e32 v68, 1.0, v68
	v_add_f32_e32 v64, 1.0, v64
	v_add_f32_e32 v69, 1.0, v69
	v_add_f32_e32 v65, 1.0, v65
	v_add_f32_e32 v70, 1.0, v70
	v_add_f32_e32 v66, 1.0, v66
	v_add_f32_e32 v67, 1.0, v67
	v_add_f32_e32 v71, 1.0, v71
	v_rcp_f32_e32 v68, v68
	v_rcp_f32_e32 v64, v64
	v_rcp_f32_e32 v65, v65
	v_rcp_f32_e32 v70, v70
	v_rcp_f32_e32 v66, v66
	v_rcp_f32_e32 v67, v67
	v_rcp_f32_e32 v71, v71
	v_rcp_f32_e32 v69, v69
	s_cmp_eq_u32 s63, 0
	v_cvt_pk_f16_f32 v67, v66, v67
	v_cvt_pk_f16_f32 v66, v64, v65
	v_cvt_pk_f16_f32 v65, v70, v71
	v_cvt_pk_f16_f32 v64, v68, v69
	s_cselect_b32 s35, s43, s45
	s_cselect_b32 s34, s42, s44
	global_store_dwordx4 v136, v[64:67], s[34:35] offset:256 nt
	v_add_u32_e32 v136, s28, v149
	s_and_b64 vcc, exec, s[4:5]
	s_mov_b64 s[34:35], -1
	s_cbranch_vccz .LBB0_1098

.LBB0_1161:
	v_mul_f32_e32 v60, 0xbfb8aa3b, v60
	v_mul_f32_e32 v56, 0xbfb8aa3b, v56
	v_mul_f32_e32 v61, 0xbfb8aa3b, v61
	v_mul_f32_e32 v57, 0xbfb8aa3b, v57
	v_mul_f32_e32 v62, 0xbfb8aa3b, v62
	v_mul_f32_e32 v58, 0xbfb8aa3b, v58
	v_mul_f32_e32 v59, 0xbfb8aa3b, v59
	v_mul_f32_e32 v63, 0xbfb8aa3b, v63
	v_exp_f32_e32 v60, v60
	v_exp_f32_e32 v56, v56
	v_exp_f32_e32 v61, v61
	v_exp_f32_e32 v57, v57
	v_exp_f32_e32 v62, v62
	v_exp_f32_e32 v58, v58
	v_exp_f32_e32 v59, v59
	v_exp_f32_e32 v63, v63
	v_add_f32_e32 v60, 1.0, v60
	v_add_f32_e32 v56, 1.0, v56
	v_add_f32_e32 v61, 1.0, v61
	v_add_f32_e32 v57, 1.0, v57
	v_add_f32_e32 v62, 1.0, v62
	v_add_f32_e32 v58, 1.0, v58
	v_add_f32_e32 v59, 1.0, v59
	v_add_f32_e32 v63, 1.0, v63
	v_rcp_f32_e32 v60, v60
	v_rcp_f32_e32 v56, v56
	v_rcp_f32_e32 v57, v57
	v_rcp_f32_e32 v62, v62
	v_rcp_f32_e32 v58, v58
	v_rcp_f32_e32 v59, v59
	v_rcp_f32_e32 v63, v63
	v_rcp_f32_e32 v61, v61
	s_cmp_eq_u32 s63, 0
	v_cvt_pk_f16_f32 v59, v58, v59
	v_cvt_pk_f16_f32 v58, v56, v57
	v_cvt_pk_f16_f32 v57, v62, v63
	v_cvt_pk_f16_f32 v56, v60, v61
	s_cselect_b32 s35, s43, s45
	s_cselect_b32 s34, s42, s44
	global_store_dwordx4 v136, v[56:59], s[34:35] nt
	s_and_b64 vcc, exec, s[4:5]
	s_mov_b64 s[34:35], -1
	s_cbranch_vccz .LBB0_1104

.LBB0_1163:
	v_mul_f32_e32 v52, 0xbfb8aa3b, v52
	v_mul_f32_e32 v48, 0xbfb8aa3b, v48
	v_mul_f32_e32 v53, 0xbfb8aa3b, v53
	v_mul_f32_e32 v49, 0xbfb8aa3b, v49
	v_mul_f32_e32 v54, 0xbfb8aa3b, v54
	v_mul_f32_e32 v50, 0xbfb8aa3b, v50
	v_mul_f32_e32 v51, 0xbfb8aa3b, v51
	v_mul_f32_e32 v55, 0xbfb8aa3b, v55
	v_exp_f32_e32 v52, v52
	v_exp_f32_e32 v48, v48
	v_exp_f32_e32 v53, v53
	v_exp_f32_e32 v49, v49
	v_exp_f32_e32 v54, v54
	v_exp_f32_e32 v50, v50
	v_exp_f32_e32 v51, v51
	v_exp_f32_e32 v55, v55
	v_add_f32_e32 v52, 1.0, v52
	v_add_f32_e32 v48, 1.0, v48
	v_add_f32_e32 v53, 1.0, v53
	v_add_f32_e32 v49, 1.0, v49
	v_add_f32_e32 v54, 1.0, v54
	v_add_f32_e32 v50, 1.0, v50
	v_add_f32_e32 v51, 1.0, v51
	v_add_f32_e32 v55, 1.0, v55
	v_rcp_f32_e32 v52, v52
	v_rcp_f32_e32 v48, v48
	v_rcp_f32_e32 v49, v49
	v_rcp_f32_e32 v54, v54
	v_rcp_f32_e32 v50, v50
	v_rcp_f32_e32 v51, v51
	v_rcp_f32_e32 v55, v55
	v_rcp_f32_e32 v53, v53
	s_cmp_eq_u32 s63, 0
	v_cvt_pk_f16_f32 v51, v50, v51
	v_cvt_pk_f16_f32 v50, v48, v49
	v_cvt_pk_f16_f32 v49, v54, v55
	v_cvt_pk_f16_f32 v48, v52, v53
	s_cselect_b32 s35, s43, s45
	s_cselect_b32 s34, s42, s44
	global_store_dwordx4 v136, v[48:51], s[34:35] offset:256 nt
	v_add_u32_e32 v136, s28, v150
	s_and_b64 vcc, exec, s[4:5]
	s_mov_b64 s[34:35], -1
	s_cbranch_vccz .LBB0_1110

.LBB0_1165:
	v_mul_f32_e32 v44, 0xbfb8aa3b, v44
	v_mul_f32_e32 v40, 0xbfb8aa3b, v40
	v_mul_f32_e32 v45, 0xbfb8aa3b, v45
	v_mul_f32_e32 v41, 0xbfb8aa3b, v41
	v_mul_f32_e32 v46, 0xbfb8aa3b, v46
	v_mul_f32_e32 v42, 0xbfb8aa3b, v42
	v_mul_f32_e32 v43, 0xbfb8aa3b, v43
	v_mul_f32_e32 v47, 0xbfb8aa3b, v47
	v_exp_f32_e32 v44, v44
	v_exp_f32_e32 v40, v40
	v_exp_f32_e32 v45, v45
	v_exp_f32_e32 v41, v41
	v_exp_f32_e32 v46, v46
	v_exp_f32_e32 v42, v42
	v_exp_f32_e32 v43, v43
	v_exp_f32_e32 v47, v47
	v_add_f32_e32 v44, 1.0, v44
	v_add_f32_e32 v40, 1.0, v40
	v_add_f32_e32 v45, 1.0, v45
	v_add_f32_e32 v41, 1.0, v41
	v_add_f32_e32 v46, 1.0, v46
	v_add_f32_e32 v42, 1.0, v42
	v_add_f32_e32 v43, 1.0, v43
	v_add_f32_e32 v47, 1.0, v47
	v_rcp_f32_e32 v44, v44
	v_rcp_f32_e32 v40, v40
	v_rcp_f32_e32 v41, v41
	v_rcp_f32_e32 v46, v46
	v_rcp_f32_e32 v42, v42
	v_rcp_f32_e32 v43, v43
	v_rcp_f32_e32 v47, v47
	v_rcp_f32_e32 v45, v45
	s_cmp_eq_u32 s63, 0
	v_cvt_pk_f16_f32 v43, v42, v43
	v_cvt_pk_f16_f32 v42, v40, v41
	v_cvt_pk_f16_f32 v41, v46, v47
	v_cvt_pk_f16_f32 v40, v44, v45
	s_cselect_b32 s35, s43, s45
	s_cselect_b32 s34, s42, s44
	global_store_dwordx4 v136, v[40:43], s[34:35] nt
	s_and_b64 vcc, exec, s[4:5]
	s_mov_b64 s[34:35], -1
	s_cbranch_vccz .LBB0_1116

.LBB0_1167:
	v_mul_f32_e32 v36, 0xbfb8aa3b, v36
	v_mul_f32_e32 v32, 0xbfb8aa3b, v32
	v_mul_f32_e32 v37, 0xbfb8aa3b, v37
	v_mul_f32_e32 v33, 0xbfb8aa3b, v33
	v_mul_f32_e32 v38, 0xbfb8aa3b, v38
	v_mul_f32_e32 v34, 0xbfb8aa3b, v34
	v_mul_f32_e32 v35, 0xbfb8aa3b, v35
	v_mul_f32_e32 v39, 0xbfb8aa3b, v39
	v_exp_f32_e32 v36, v36
	v_exp_f32_e32 v32, v32
	v_exp_f32_e32 v37, v37
	v_exp_f32_e32 v33, v33
	v_exp_f32_e32 v38, v38
	v_exp_f32_e32 v34, v34
	v_exp_f32_e32 v35, v35
	v_exp_f32_e32 v39, v39
	v_add_f32_e32 v36, 1.0, v36
	v_add_f32_e32 v32, 1.0, v32
	v_add_f32_e32 v37, 1.0, v37
	v_add_f32_e32 v33, 1.0, v33
	v_add_f32_e32 v38, 1.0, v38
	v_add_f32_e32 v34, 1.0, v34
	v_add_f32_e32 v35, 1.0, v35
	v_add_f32_e32 v39, 1.0, v39
	v_rcp_f32_e32 v36, v36
	v_rcp_f32_e32 v32, v32
	v_rcp_f32_e32 v33, v33
	v_rcp_f32_e32 v38, v38
	v_rcp_f32_e32 v34, v34
	v_rcp_f32_e32 v35, v35
	v_rcp_f32_e32 v39, v39
	v_rcp_f32_e32 v37, v37
	s_cmp_eq_u32 s63, 0
	v_cvt_pk_f16_f32 v35, v34, v35
	v_cvt_pk_f16_f32 v34, v32, v33
	v_cvt_pk_f16_f32 v33, v38, v39
	v_cvt_pk_f16_f32 v32, v36, v37
	s_cselect_b32 s35, s43, s45
	s_cselect_b32 s34, s42, s44
	global_store_dwordx4 v136, v[32:35], s[34:35] offset:256 nt
	v_add_u32_e32 v136, s28, v151
	s_and_b64 vcc, exec, s[4:5]
	s_mov_b64 s[34:35], -1
	s_cbranch_vccz .LBB0_1122

.LBB0_1169:
	v_mul_f32_e32 v28, 0xbfb8aa3b, v28
	v_mul_f32_e32 v24, 0xbfb8aa3b, v24
	v_mul_f32_e32 v29, 0xbfb8aa3b, v29
	v_mul_f32_e32 v25, 0xbfb8aa3b, v25
	v_mul_f32_e32 v30, 0xbfb8aa3b, v30
	v_mul_f32_e32 v26, 0xbfb8aa3b, v26
	v_mul_f32_e32 v27, 0xbfb8aa3b, v27
	v_mul_f32_e32 v31, 0xbfb8aa3b, v31
	v_exp_f32_e32 v28, v28
	v_exp_f32_e32 v24, v24
	v_exp_f32_e32 v29, v29
	v_exp_f32_e32 v25, v25
	v_exp_f32_e32 v30, v30
	v_exp_f32_e32 v26, v26
	v_exp_f32_e32 v27, v27
	v_exp_f32_e32 v31, v31
	v_add_f32_e32 v28, 1.0, v28
	v_add_f32_e32 v24, 1.0, v24
	v_add_f32_e32 v29, 1.0, v29
	v_add_f32_e32 v25, 1.0, v25
	v_add_f32_e32 v30, 1.0, v30
	v_add_f32_e32 v26, 1.0, v26
	v_add_f32_e32 v27, 1.0, v27
	v_add_f32_e32 v31, 1.0, v31
	v_rcp_f32_e32 v28, v28
	v_rcp_f32_e32 v24, v24
	v_rcp_f32_e32 v25, v25
	v_rcp_f32_e32 v30, v30
	v_rcp_f32_e32 v26, v26
	v_rcp_f32_e32 v27, v27
	v_rcp_f32_e32 v31, v31
	v_rcp_f32_e32 v29, v29
	s_cmp_eq_u32 s63, 0
	v_cvt_pk_f16_f32 v27, v26, v27
	v_cvt_pk_f16_f32 v26, v24, v25
	v_cvt_pk_f16_f32 v25, v30, v31
	v_cvt_pk_f16_f32 v24, v28, v29
	s_cselect_b32 s35, s43, s45
	s_cselect_b32 s34, s42, s44
	global_store_dwordx4 v136, v[24:27], s[34:35] nt
	s_and_b64 vcc, exec, s[4:5]
	s_mov_b64 s[34:35], -1
	s_cbranch_vccz .LBB0_1128

.LBB0_1171:
	v_mul_f32_e32 v20, 0xbfb8aa3b, v20
	v_mul_f32_e32 v16, 0xbfb8aa3b, v16
	v_mul_f32_e32 v21, 0xbfb8aa3b, v21
	v_mul_f32_e32 v17, 0xbfb8aa3b, v17
	v_mul_f32_e32 v22, 0xbfb8aa3b, v22
	v_mul_f32_e32 v18, 0xbfb8aa3b, v18
	v_mul_f32_e32 v19, 0xbfb8aa3b, v19
	v_mul_f32_e32 v23, 0xbfb8aa3b, v23
	v_exp_f32_e32 v20, v20
	v_exp_f32_e32 v16, v16
	v_exp_f32_e32 v21, v21
	v_exp_f32_e32 v17, v17
	v_exp_f32_e32 v22, v22
	v_exp_f32_e32 v18, v18
	v_exp_f32_e32 v19, v19
	v_exp_f32_e32 v23, v23
	v_add_f32_e32 v20, 1.0, v20
	v_add_f32_e32 v16, 1.0, v16
	v_add_f32_e32 v21, 1.0, v21
	v_add_f32_e32 v17, 1.0, v17
	v_add_f32_e32 v22, 1.0, v22
	v_add_f32_e32 v18, 1.0, v18
	v_add_f32_e32 v19, 1.0, v19
	v_add_f32_e32 v23, 1.0, v23
	v_rcp_f32_e32 v20, v20
	v_rcp_f32_e32 v16, v16
	v_rcp_f32_e32 v17, v17
	v_rcp_f32_e32 v22, v22
	v_rcp_f32_e32 v18, v18
	v_rcp_f32_e32 v19, v19
	v_rcp_f32_e32 v23, v23
	v_rcp_f32_e32 v21, v21
	s_cmp_eq_u32 s63, 0
	v_cvt_pk_f16_f32 v19, v18, v19
	v_cvt_pk_f16_f32 v18, v16, v17
	v_cvt_pk_f16_f32 v17, v22, v23
	v_cvt_pk_f16_f32 v16, v20, v21
	s_cselect_b32 s35, s43, s45
	s_cselect_b32 s34, s42, s44
	global_store_dwordx4 v136, v[16:19], s[34:35] offset:256 nt
	v_add_u32_e32 v136, s28, v152
	s_and_b64 vcc, exec, s[4:5]
	s_mov_b64 s[34:35], -1
	s_cbranch_vccz .LBB0_1134

.LBB0_1173:
	v_mul_f32_e32 v12, 0xbfb8aa3b, v12
	v_mul_f32_e32 v8, 0xbfb8aa3b, v8
	v_mul_f32_e32 v13, 0xbfb8aa3b, v13
	v_mul_f32_e32 v9, 0xbfb8aa3b, v9
	v_mul_f32_e32 v14, 0xbfb8aa3b, v14
	v_mul_f32_e32 v10, 0xbfb8aa3b, v10
	v_mul_f32_e32 v11, 0xbfb8aa3b, v11
	v_mul_f32_e32 v15, 0xbfb8aa3b, v15
	v_exp_f32_e32 v12, v12
	v_exp_f32_e32 v8, v8
	v_exp_f32_e32 v13, v13
	v_exp_f32_e32 v9, v9
	v_exp_f32_e32 v14, v14
	v_exp_f32_e32 v10, v10
	v_exp_f32_e32 v11, v11
	v_exp_f32_e32 v15, v15
	v_add_f32_e32 v12, 1.0, v12
	v_add_f32_e32 v8, 1.0, v8
	v_add_f32_e32 v13, 1.0, v13
	v_add_f32_e32 v9, 1.0, v9
	v_add_f32_e32 v14, 1.0, v14
	v_add_f32_e32 v10, 1.0, v10
	v_add_f32_e32 v11, 1.0, v11
	v_add_f32_e32 v15, 1.0, v15
	v_rcp_f32_e32 v12, v12
	v_rcp_f32_e32 v8, v8
	v_rcp_f32_e32 v9, v9
	v_rcp_f32_e32 v14, v14
	v_rcp_f32_e32 v10, v10
	v_rcp_f32_e32 v11, v11
	v_rcp_f32_e32 v15, v15
	v_rcp_f32_e32 v13, v13
	s_cmp_eq_u32 s63, 0
	v_cvt_pk_f16_f32 v11, v10, v11
	v_cvt_pk_f16_f32 v10, v8, v9
	v_cvt_pk_f16_f32 v9, v14, v15
	v_cvt_pk_f16_f32 v8, v12, v13
	s_cselect_b32 s29, s43, s45
	s_cselect_b32 s28, s42, s44
	global_store_dwordx4 v136, v[8:11], s[28:29] nt
	s_and_b64 vcc, exec, s[4:5]
	s_mov_b64 s[4:5], -1
	s_cbranch_vccz .LBB0_1140

.LBB0_1175:
	v_mul_f32_e32 v4, 0xbfb8aa3b, v4
	v_mul_f32_e32 v0, 0xbfb8aa3b, v0
	v_mul_f32_e32 v5, 0xbfb8aa3b, v5
	v_mul_f32_e32 v1, 0xbfb8aa3b, v1
	v_mul_f32_e32 v6, 0xbfb8aa3b, v6
	v_mul_f32_e32 v2, 0xbfb8aa3b, v2
	v_mul_f32_e32 v3, 0xbfb8aa3b, v3
	v_mul_f32_e32 v7, 0xbfb8aa3b, v7
	v_exp_f32_e32 v4, v4
	v_exp_f32_e32 v0, v0
	v_exp_f32_e32 v5, v5
	v_exp_f32_e32 v1, v1
	v_exp_f32_e32 v6, v6
	v_exp_f32_e32 v2, v2
	v_exp_f32_e32 v3, v3
	v_exp_f32_e32 v7, v7
	v_add_f32_e32 v4, 1.0, v4
	v_add_f32_e32 v0, 1.0, v0
	v_add_f32_e32 v5, 1.0, v5
	v_add_f32_e32 v1, 1.0, v1
	v_add_f32_e32 v6, 1.0, v6
	v_add_f32_e32 v2, 1.0, v2
	v_add_f32_e32 v3, 1.0, v3
	v_add_f32_e32 v7, 1.0, v7
	v_rcp_f32_e32 v4, v4
	v_rcp_f32_e32 v0, v0
	v_rcp_f32_e32 v1, v1
	v_rcp_f32_e32 v6, v6
	v_rcp_f32_e32 v2, v2
	v_rcp_f32_e32 v3, v3
	v_rcp_f32_e32 v7, v7
	v_rcp_f32_e32 v5, v5
	s_cmp_eq_u32 s63, 0
	v_cvt_pk_f16_f32 v3, v2, v3
	v_cvt_pk_f16_f32 v2, v0, v1
	v_cvt_pk_f16_f32 v1, v6, v7
	v_cvt_pk_f16_f32 v0, v4, v5
	s_cselect_b32 s5, s43, s45
	s_cselect_b32 s4, s42, s44
	global_store_dwordx4 v136, v[0:3], s[4:5] offset:256 nt
	s_andn2_b64 vcc, exec, s[40:41]
	s_mov_b64 s[4:5], -1
	s_cbranch_vccnz .LBB0_1029

.Lsh_k01:
	s_cmp_eq_u32 s63, 0
	s_cselect_b32 s5, s43, s45
	s_cselect_b32 s4, s42, s44
	v_mov_b32_e32 v156, v136
	v_add_u32_e32 v157, 0x8000, v136
	v_add_u32_e32 v158, 0x10000, v136
	v_add_u32_e32 v159, 0x18000, v136
	v_add_u32_e32 v160, 0x40000, v136
	v_add_u32_e32 v161, 0x48000, v136
	v_add_u32_e32 v162, 0x50000, v136
	v_add_u32_e32 v163, 0x58000, v136
	v_mul_f32_e32 v124, 0xbfb8aa3b, v124
	v_mul_f32_e32 v120, 0xbfb8aa3b, v120
	v_mul_f32_e32 v125, 0xbfb8aa3b, v125
	v_mul_f32_e32 v121, 0xbfb8aa3b, v121
	v_mul_f32_e32 v126, 0xbfb8aa3b, v126
	v_mul_f32_e32 v122, 0xbfb8aa3b, v122
	v_mul_f32_e32 v123, 0xbfb8aa3b, v123
	v_mul_f32_e32 v127, 0xbfb8aa3b, v127
	v_exp_f32_e32 v124, v124
	v_exp_f32_e32 v120, v120
	v_exp_f32_e32 v125, v125
	v_exp_f32_e32 v121, v121
	v_exp_f32_e32 v126, v126
	v_exp_f32_e32 v122, v122
	v_exp_f32_e32 v123, v123
	v_exp_f32_e32 v127, v127
	v_add_f32_e32 v124, 1.0, v124
	v_add_f32_e32 v120, 1.0, v120
	v_add_f32_e32 v125, 1.0, v125
	v_add_f32_e32 v121, 1.0, v121
	v_add_f32_e32 v126, 1.0, v126
	v_add_f32_e32 v122, 1.0, v122
	v_add_f32_e32 v123, 1.0, v123
	v_add_f32_e32 v127, 1.0, v127
	v_rcp_f32_e32 v124, v124
	v_rcp_f32_e32 v120, v120
	v_rcp_f32_e32 v121, v121
	v_rcp_f32_e32 v126, v126
	v_rcp_f32_e32 v122, v122
	v_rcp_f32_e32 v123, v123
	v_rcp_f32_e32 v127, v127
	v_rcp_f32_e32 v125, v125
	s_nop 0
	v_cvt_pk_f16_f32 v123, v122, v123
	v_cvt_pk_f16_f32 v122, v120, v121
	v_cvt_pk_f16_f32 v121, v126, v127
	v_cvt_pk_f16_f32 v120, v124, v125
	global_store_dwordx4 v156, v[120:123], s[4:5] nt
	v_mul_f32_e32 v116, 0xbfb8aa3b, v116
	v_mul_f32_e32 v112, 0xbfb8aa3b, v112
	v_mul_f32_e32 v117, 0xbfb8aa3b, v117
	v_mul_f32_e32 v113, 0xbfb8aa3b, v113
	v_mul_f32_e32 v118, 0xbfb8aa3b, v118
	v_mul_f32_e32 v114, 0xbfb8aa3b, v114
	v_mul_f32_e32 v115, 0xbfb8aa3b, v115
	v_mul_f32_e32 v119, 0xbfb8aa3b, v119
	v_exp_f32_e32 v116, v116
	v_exp_f32_e32 v112, v112
	v_exp_f32_e32 v117, v117
	v_exp_f32_e32 v113, v113
	v_exp_f32_e32 v118, v118
	v_exp_f32_e32 v114, v114
	v_exp_f32_e32 v115, v115
	v_exp_f32_e32 v119, v119
	v_add_f32_e32 v116, 1.0, v116
	v_add_f32_e32 v112, 1.0, v112
	v_add_f32_e32 v117, 1.0, v117
	v_add_f32_e32 v113, 1.0, v113
	v_add_f32_e32 v118, 1.0, v118
	v_add_f32_e32 v114, 1.0, v114
	v_add_f32_e32 v115, 1.0, v115
	v_add_f32_e32 v119, 1.0, v119
	v_rcp_f32_e32 v116, v116
	v_rcp_f32_e32 v112, v112
	v_rcp_f32_e32 v113, v113
	v_rcp_f32_e32 v118, v118
	v_rcp_f32_e32 v114, v114
	v_rcp_f32_e32 v115, v115
	v_rcp_f32_e32 v119, v119
	v_rcp_f32_e32 v117, v117
	s_nop 0
	v_cvt_pk_f16_f32 v115, v114, v115
	v_cvt_pk_f16_f32 v114, v112, v113
	v_cvt_pk_f16_f32 v113, v118, v119
	v_cvt_pk_f16_f32 v112, v116, v117
	global_store_dwordx4 v156, v[112:115], s[4:5] offset:256 nt
	v_mul_f32_e32 v108, 0xbfb8aa3b, v108
	v_mul_f32_e32 v104, 0xbfb8aa3b, v104
	v_mul_f32_e32 v109, 0xbfb8aa3b, v109
	v_mul_f32_e32 v105, 0xbfb8aa3b, v105
	v_mul_f32_e32 v110, 0xbfb8aa3b, v110
	v_mul_f32_e32 v106, 0xbfb8aa3b, v106
	v_mul_f32_e32 v107, 0xbfb8aa3b, v107
	v_mul_f32_e32 v111, 0xbfb8aa3b, v111
	v_exp_f32_e32 v108, v108
	v_exp_f32_e32 v104, v104
	v_exp_f32_e32 v109, v109
	v_exp_f32_e32 v105, v105
	v_exp_f32_e32 v110, v110
	v_exp_f32_e32 v106, v106
	v_exp_f32_e32 v107, v107
	v_exp_f32_e32 v111, v111
	v_add_f32_e32 v108, 1.0, v108
	v_add_f32_e32 v104, 1.0, v104
	v_add_f32_e32 v109, 1.0, v109
	v_add_f32_e32 v105, 1.0, v105
	v_add_f32_e32 v110, 1.0, v110
	v_add_f32_e32 v106, 1.0, v106
	v_add_f32_e32 v107, 1.0, v107
	v_add_f32_e32 v111, 1.0, v111
	v_rcp_f32_e32 v108, v108
	v_rcp_f32_e32 v104, v104
	v_rcp_f32_e32 v105, v105
	v_rcp_f32_e32 v110, v110
	v_rcp_f32_e32 v106, v106
	v_rcp_f32_e32 v107, v107
	v_rcp_f32_e32 v111, v111
	v_rcp_f32_e32 v109, v109
	s_nop 0
	v_cvt_pk_f16_f32 v107, v106, v107
	v_cvt_pk_f16_f32 v106, v104, v105
	v_cvt_pk_f16_f32 v105, v110, v111
	v_cvt_pk_f16_f32 v104, v108, v109
	global_store_dwordx4 v157, v[104:107], s[4:5] nt
	v_mul_f32_e32 v100, 0xbfb8aa3b, v100
	v_mul_f32_e32 v96, 0xbfb8aa3b, v96
	v_mul_f32_e32 v101, 0xbfb8aa3b, v101
	v_mul_f32_e32 v97, 0xbfb8aa3b, v97
	v_mul_f32_e32 v102, 0xbfb8aa3b, v102
	v_mul_f32_e32 v98, 0xbfb8aa3b, v98
	v_mul_f32_e32 v99, 0xbfb8aa3b, v99
	v_mul_f32_e32 v103, 0xbfb8aa3b, v103
	v_exp_f32_e32 v100, v100
	v_exp_f32_e32 v96, v96
	v_exp_f32_e32 v101, v101
	v_exp_f32_e32 v97, v97
	v_exp_f32_e32 v102, v102
	v_exp_f32_e32 v98, v98
	v_exp_f32_e32 v99, v99
	v_exp_f32_e32 v103, v103
	v_add_f32_e32 v100, 1.0, v100
	v_add_f32_e32 v96, 1.0, v96
	v_add_f32_e32 v101, 1.0, v101
	v_add_f32_e32 v97, 1.0, v97
	v_add_f32_e32 v102, 1.0, v102
	v_add_f32_e32 v98, 1.0, v98
	v_add_f32_e32 v99, 1.0, v99
	v_add_f32_e32 v103, 1.0, v103
	v_rcp_f32_e32 v100, v100
	v_rcp_f32_e32 v96, v96
	v_rcp_f32_e32 v97, v97
	v_rcp_f32_e32 v102, v102
	v_rcp_f32_e32 v98, v98
	v_rcp_f32_e32 v99, v99
	v_rcp_f32_e32 v103, v103
	v_rcp_f32_e32 v101, v101
	s_nop 0
	v_cvt_pk_f16_f32 v99, v98, v99
	v_cvt_pk_f16_f32 v98, v96, v97
	v_cvt_pk_f16_f32 v97, v102, v103
	v_cvt_pk_f16_f32 v96, v100, v101
	global_store_dwordx4 v157, v[96:99], s[4:5] offset:256 nt
	v_mul_f32_e32 v92, 0xbfb8aa3b, v92
	v_mul_f32_e32 v88, 0xbfb8aa3b, v88
	v_mul_f32_e32 v93, 0xbfb8aa3b, v93
	v_mul_f32_e32 v89, 0xbfb8aa3b, v89
	v_mul_f32_e32 v94, 0xbfb8aa3b, v94
	v_mul_f32_e32 v90, 0xbfb8aa3b, v90
	v_mul_f32_e32 v91, 0xbfb8aa3b, v91
	v_mul_f32_e32 v95, 0xbfb8aa3b, v95
	v_exp_f32_e32 v92, v92
	v_exp_f32_e32 v88, v88
	v_exp_f32_e32 v93, v93
	v_exp_f32_e32 v89, v89
	v_exp_f32_e32 v94, v94
	v_exp_f32_e32 v90, v90
	v_exp_f32_e32 v91, v91
	v_exp_f32_e32 v95, v95
	v_add_f32_e32 v92, 1.0, v92
	v_add_f32_e32 v88, 1.0, v88
	v_add_f32_e32 v93, 1.0, v93
	v_add_f32_e32 v89, 1.0, v89
	v_add_f32_e32 v94, 1.0, v94
	v_add_f32_e32 v90, 1.0, v90
	v_add_f32_e32 v91, 1.0, v91
	v_add_f32_e32 v95, 1.0, v95
	v_rcp_f32_e32 v92, v92
	v_rcp_f32_e32 v88, v88
	v_rcp_f32_e32 v89, v89
	v_rcp_f32_e32 v94, v94
	v_rcp_f32_e32 v90, v90
	v_rcp_f32_e32 v91, v91
	v_rcp_f32_e32 v95, v95
	v_rcp_f32_e32 v93, v93
	s_nop 0
	v_cvt_pk_f16_f32 v91, v90, v91
	v_cvt_pk_f16_f32 v90, v88, v89
	v_cvt_pk_f16_f32 v89, v94, v95
	v_cvt_pk_f16_f32 v88, v92, v93
	global_store_dwordx4 v158, v[88:91], s[4:5] nt
	v_mul_f32_e32 v84, 0xbfb8aa3b, v84
	v_mul_f32_e32 v80, 0xbfb8aa3b, v80
	v_mul_f32_e32 v85, 0xbfb8aa3b, v85
	v_mul_f32_e32 v81, 0xbfb8aa3b, v81
	v_mul_f32_e32 v86, 0xbfb8aa3b, v86
	v_mul_f32_e32 v82, 0xbfb8aa3b, v82
	v_mul_f32_e32 v83, 0xbfb8aa3b, v83
	v_mul_f32_e32 v87, 0xbfb8aa3b, v87
	v_exp_f32_e32 v84, v84
	v_exp_f32_e32 v80, v80
	v_exp_f32_e32 v85, v85
	v_exp_f32_e32 v81, v81
	v_exp_f32_e32 v86, v86
	v_exp_f32_e32 v82, v82
	v_exp_f32_e32 v83, v83
	v_exp_f32_e32 v87, v87
	v_add_f32_e32 v84, 1.0, v84
	v_add_f32_e32 v80, 1.0, v80
	v_add_f32_e32 v85, 1.0, v85
	v_add_f32_e32 v81, 1.0, v81
	v_add_f32_e32 v86, 1.0, v86
	v_add_f32_e32 v82, 1.0, v82
	v_add_f32_e32 v83, 1.0, v83
	v_add_f32_e32 v87, 1.0, v87
	v_rcp_f32_e32 v84, v84
	v_rcp_f32_e32 v80, v80
	v_rcp_f32_e32 v81, v81
	v_rcp_f32_e32 v86, v86
	v_rcp_f32_e32 v82, v82
	v_rcp_f32_e32 v83, v83
	v_rcp_f32_e32 v87, v87
	v_rcp_f32_e32 v85, v85
	s_nop 0
	v_cvt_pk_f16_f32 v83, v82, v83
	v_cvt_pk_f16_f32 v82, v80, v81
	v_cvt_pk_f16_f32 v81, v86, v87
	v_cvt_pk_f16_f32 v80, v84, v85
	global_store_dwordx4 v158, v[80:83], s[4:5] offset:256 nt
	v_mul_f32_e32 v76, 0xbfb8aa3b, v76
	v_mul_f32_e32 v72, 0xbfb8aa3b, v72
	v_mul_f32_e32 v77, 0xbfb8aa3b, v77
	v_mul_f32_e32 v73, 0xbfb8aa3b, v73
	v_mul_f32_e32 v78, 0xbfb8aa3b, v78
	v_mul_f32_e32 v74, 0xbfb8aa3b, v74
	v_mul_f32_e32 v75, 0xbfb8aa3b, v75
	v_mul_f32_e32 v79, 0xbfb8aa3b, v79
	v_exp_f32_e32 v76, v76
	v_exp_f32_e32 v72, v72
	v_exp_f32_e32 v77, v77
	v_exp_f32_e32 v73, v73
	v_exp_f32_e32 v78, v78
	v_exp_f32_e32 v74, v74
	v_exp_f32_e32 v75, v75
	v_exp_f32_e32 v79, v79
	v_add_f32_e32 v76, 1.0, v76
	v_add_f32_e32 v72, 1.0, v72
	v_add_f32_e32 v77, 1.0, v77
	v_add_f32_e32 v73, 1.0, v73
	v_add_f32_e32 v78, 1.0, v78
	v_add_f32_e32 v74, 1.0, v74
	v_add_f32_e32 v75, 1.0, v75
	v_add_f32_e32 v79, 1.0, v79
	v_rcp_f32_e32 v76, v76
	v_rcp_f32_e32 v72, v72
	v_rcp_f32_e32 v73, v73
	v_rcp_f32_e32 v78, v78
	v_rcp_f32_e32 v74, v74
	v_rcp_f32_e32 v75, v75
	v_rcp_f32_e32 v79, v79
	v_rcp_f32_e32 v77, v77
	s_nop 0
	v_cvt_pk_f16_f32 v75, v74, v75
	v_cvt_pk_f16_f32 v74, v72, v73
	v_cvt_pk_f16_f32 v73, v78, v79
	v_cvt_pk_f16_f32 v72, v76, v77
	global_store_dwordx4 v159, v[72:75], s[4:5] nt
	v_mul_f32_e32 v68, 0xbfb8aa3b, v68
	v_mul_f32_e32 v64, 0xbfb8aa3b, v64
	v_mul_f32_e32 v69, 0xbfb8aa3b, v69
	v_mul_f32_e32 v65, 0xbfb8aa3b, v65
	v_mul_f32_e32 v70, 0xbfb8aa3b, v70
	v_mul_f32_e32 v66, 0xbfb8aa3b, v66
	v_mul_f32_e32 v67, 0xbfb8aa3b, v67
	v_mul_f32_e32 v71, 0xbfb8aa3b, v71
	v_exp_f32_e32 v68, v68
	v_exp_f32_e32 v64, v64
	v_exp_f32_e32 v69, v69
	v_exp_f32_e32 v65, v65
	v_exp_f32_e32 v70, v70
	v_exp_f32_e32 v66, v66
	v_exp_f32_e32 v67, v67
	v_exp_f32_e32 v71, v71
	v_add_f32_e32 v68, 1.0, v68
	v_add_f32_e32 v64, 1.0, v64
	v_add_f32_e32 v69, 1.0, v69
	v_add_f32_e32 v65, 1.0, v65
	v_add_f32_e32 v70, 1.0, v70
	v_add_f32_e32 v66, 1.0, v66
	v_add_f32_e32 v67, 1.0, v67
	v_add_f32_e32 v71, 1.0, v71
	v_rcp_f32_e32 v68, v68
	v_rcp_f32_e32 v64, v64
	v_rcp_f32_e32 v65, v65
	v_rcp_f32_e32 v70, v70
	v_rcp_f32_e32 v66, v66
	v_rcp_f32_e32 v67, v67
	v_rcp_f32_e32 v71, v71
	v_rcp_f32_e32 v69, v69
	s_nop 0
	v_cvt_pk_f16_f32 v67, v66, v67
	v_cvt_pk_f16_f32 v66, v64, v65
	v_cvt_pk_f16_f32 v65, v70, v71
	v_cvt_pk_f16_f32 v64, v68, v69
	global_store_dwordx4 v159, v[64:67], s[4:5] offset:256 nt
	v_mul_f32_e32 v60, 0xbfb8aa3b, v60
	v_mul_f32_e32 v56, 0xbfb8aa3b, v56
	v_mul_f32_e32 v61, 0xbfb8aa3b, v61
	v_mul_f32_e32 v57, 0xbfb8aa3b, v57
	v_mul_f32_e32 v62, 0xbfb8aa3b, v62
	v_mul_f32_e32 v58, 0xbfb8aa3b, v58
	v_mul_f32_e32 v59, 0xbfb8aa3b, v59
	v_mul_f32_e32 v63, 0xbfb8aa3b, v63
	v_exp_f32_e32 v60, v60
	v_exp_f32_e32 v56, v56
	v_exp_f32_e32 v61, v61
	v_exp_f32_e32 v57, v57
	v_exp_f32_e32 v62, v62
	v_exp_f32_e32 v58, v58
	v_exp_f32_e32 v59, v59
	v_exp_f32_e32 v63, v63
	v_add_f32_e32 v60, 1.0, v60
	v_add_f32_e32 v56, 1.0, v56
	v_add_f32_e32 v61, 1.0, v61
	v_add_f32_e32 v57, 1.0, v57
	v_add_f32_e32 v62, 1.0, v62
	v_add_f32_e32 v58, 1.0, v58
	v_add_f32_e32 v59, 1.0, v59
	v_add_f32_e32 v63, 1.0, v63
	v_rcp_f32_e32 v60, v60
	v_rcp_f32_e32 v56, v56
	v_rcp_f32_e32 v57, v57
	v_rcp_f32_e32 v62, v62
	v_rcp_f32_e32 v58, v58
	v_rcp_f32_e32 v59, v59
	v_rcp_f32_e32 v63, v63
	v_rcp_f32_e32 v61, v61
	s_nop 0
	v_cvt_pk_f16_f32 v59, v58, v59
	v_cvt_pk_f16_f32 v58, v56, v57
	v_cvt_pk_f16_f32 v57, v62, v63
	v_cvt_pk_f16_f32 v56, v60, v61
	global_store_dwordx4 v160, v[56:59], s[4:5] nt
	v_mul_f32_e32 v52, 0xbfb8aa3b, v52
	v_mul_f32_e32 v48, 0xbfb8aa3b, v48
	v_mul_f32_e32 v53, 0xbfb8aa3b, v53
	v_mul_f32_e32 v49, 0xbfb8aa3b, v49
	v_mul_f32_e32 v54, 0xbfb8aa3b, v54
	v_mul_f32_e32 v50, 0xbfb8aa3b, v50
	v_mul_f32_e32 v51, 0xbfb8aa3b, v51
	v_mul_f32_e32 v55, 0xbfb8aa3b, v55
	v_exp_f32_e32 v52, v52
	v_exp_f32_e32 v48, v48
	v_exp_f32_e32 v53, v53
	v_exp_f32_e32 v49, v49
	v_exp_f32_e32 v54, v54
	v_exp_f32_e32 v50, v50
	v_exp_f32_e32 v51, v51
	v_exp_f32_e32 v55, v55
	v_add_f32_e32 v52, 1.0, v52
	v_add_f32_e32 v48, 1.0, v48
	v_add_f32_e32 v53, 1.0, v53
	v_add_f32_e32 v49, 1.0, v49
	v_add_f32_e32 v54, 1.0, v54
	v_add_f32_e32 v50, 1.0, v50
	v_add_f32_e32 v51, 1.0, v51
	v_add_f32_e32 v55, 1.0, v55
	v_rcp_f32_e32 v52, v52
	v_rcp_f32_e32 v48, v48
	v_rcp_f32_e32 v49, v49
	v_rcp_f32_e32 v54, v54
	v_rcp_f32_e32 v50, v50
	v_rcp_f32_e32 v51, v51
	v_rcp_f32_e32 v55, v55
	v_rcp_f32_e32 v53, v53
	s_nop 0
	v_cvt_pk_f16_f32 v51, v50, v51
	v_cvt_pk_f16_f32 v50, v48, v49
	v_cvt_pk_f16_f32 v49, v54, v55
	v_cvt_pk_f16_f32 v48, v52, v53
	global_store_dwordx4 v160, v[48:51], s[4:5] offset:256 nt
	v_mul_f32_e32 v44, 0xbfb8aa3b, v44
	v_mul_f32_e32 v40, 0xbfb8aa3b, v40
	v_mul_f32_e32 v45, 0xbfb8aa3b, v45
	v_mul_f32_e32 v41, 0xbfb8aa3b, v41
	v_mul_f32_e32 v46, 0xbfb8aa3b, v46
	v_mul_f32_e32 v42, 0xbfb8aa3b, v42
	v_mul_f32_e32 v43, 0xbfb8aa3b, v43
	v_mul_f32_e32 v47, 0xbfb8aa3b, v47
	v_exp_f32_e32 v44, v44
	v_exp_f32_e32 v40, v40
	v_exp_f32_e32 v45, v45
	v_exp_f32_e32 v41, v41
	v_exp_f32_e32 v46, v46
	v_exp_f32_e32 v42, v42
	v_exp_f32_e32 v43, v43
	v_exp_f32_e32 v47, v47
	v_add_f32_e32 v44, 1.0, v44
	v_add_f32_e32 v40, 1.0, v40
	v_add_f32_e32 v45, 1.0, v45
	v_add_f32_e32 v41, 1.0, v41
	v_add_f32_e32 v46, 1.0, v46
	v_add_f32_e32 v42, 1.0, v42
	v_add_f32_e32 v43, 1.0, v43
	v_add_f32_e32 v47, 1.0, v47
	v_rcp_f32_e32 v44, v44
	v_rcp_f32_e32 v40, v40
	v_rcp_f32_e32 v41, v41
	v_rcp_f32_e32 v46, v46
	v_rcp_f32_e32 v42, v42
	v_rcp_f32_e32 v43, v43
	v_rcp_f32_e32 v47, v47
	v_rcp_f32_e32 v45, v45
	s_nop 0
	v_cvt_pk_f16_f32 v43, v42, v43
	v_cvt_pk_f16_f32 v42, v40, v41
	v_cvt_pk_f16_f32 v41, v46, v47
	v_cvt_pk_f16_f32 v40, v44, v45
	global_store_dwordx4 v161, v[40:43], s[4:5] nt
	v_mul_f32_e32 v36, 0xbfb8aa3b, v36
	v_mul_f32_e32 v32, 0xbfb8aa3b, v32
	v_mul_f32_e32 v37, 0xbfb8aa3b, v37
	v_mul_f32_e32 v33, 0xbfb8aa3b, v33
	v_mul_f32_e32 v38, 0xbfb8aa3b, v38
	v_mul_f32_e32 v34, 0xbfb8aa3b, v34
	v_mul_f32_e32 v35, 0xbfb8aa3b, v35
	v_mul_f32_e32 v39, 0xbfb8aa3b, v39
	v_exp_f32_e32 v36, v36
	v_exp_f32_e32 v32, v32
	v_exp_f32_e32 v37, v37
	v_exp_f32_e32 v33, v33
	v_exp_f32_e32 v38, v38
	v_exp_f32_e32 v34, v34
	v_exp_f32_e32 v35, v35
	v_exp_f32_e32 v39, v39
	v_add_f32_e32 v36, 1.0, v36
	v_add_f32_e32 v32, 1.0, v32
	v_add_f32_e32 v37, 1.0, v37
	v_add_f32_e32 v33, 1.0, v33
	v_add_f32_e32 v38, 1.0, v38
	v_add_f32_e32 v34, 1.0, v34
	v_add_f32_e32 v35, 1.0, v35
	v_add_f32_e32 v39, 1.0, v39
	v_rcp_f32_e32 v36, v36
	v_rcp_f32_e32 v32, v32
	v_rcp_f32_e32 v33, v33
	v_rcp_f32_e32 v38, v38
	v_rcp_f32_e32 v34, v34
	v_rcp_f32_e32 v35, v35
	v_rcp_f32_e32 v39, v39
	v_rcp_f32_e32 v37, v37
	s_nop 0
	v_cvt_pk_f16_f32 v35, v34, v35
	v_cvt_pk_f16_f32 v34, v32, v33
	v_cvt_pk_f16_f32 v33, v38, v39
	v_cvt_pk_f16_f32 v32, v36, v37
	global_store_dwordx4 v161, v[32:35], s[4:5] offset:256 nt
	v_mul_f32_e32 v28, 0xbfb8aa3b, v28
	v_mul_f32_e32 v24, 0xbfb8aa3b, v24
	v_mul_f32_e32 v29, 0xbfb8aa3b, v29
	v_mul_f32_e32 v25, 0xbfb8aa3b, v25
	v_mul_f32_e32 v30, 0xbfb8aa3b, v30
	v_mul_f32_e32 v26, 0xbfb8aa3b, v26
	v_mul_f32_e32 v27, 0xbfb8aa3b, v27
	v_mul_f32_e32 v31, 0xbfb8aa3b, v31
	v_exp_f32_e32 v28, v28
	v_exp_f32_e32 v24, v24
	v_exp_f32_e32 v29, v29
	v_exp_f32_e32 v25, v25
	v_exp_f32_e32 v30, v30
	v_exp_f32_e32 v26, v26
	v_exp_f32_e32 v27, v27
	v_exp_f32_e32 v31, v31
	v_add_f32_e32 v28, 1.0, v28
	v_add_f32_e32 v24, 1.0, v24
	v_add_f32_e32 v29, 1.0, v29
	v_add_f32_e32 v25, 1.0, v25
	v_add_f32_e32 v30, 1.0, v30
	v_add_f32_e32 v26, 1.0, v26
	v_add_f32_e32 v27, 1.0, v27
	v_add_f32_e32 v31, 1.0, v31
	v_rcp_f32_e32 v28, v28
	v_rcp_f32_e32 v24, v24
	v_rcp_f32_e32 v25, v25
	v_rcp_f32_e32 v30, v30
	v_rcp_f32_e32 v26, v26
	v_rcp_f32_e32 v27, v27
	v_rcp_f32_e32 v31, v31
	v_rcp_f32_e32 v29, v29
	s_nop 0
	v_cvt_pk_f16_f32 v27, v26, v27
	v_cvt_pk_f16_f32 v26, v24, v25
	v_cvt_pk_f16_f32 v25, v30, v31
	v_cvt_pk_f16_f32 v24, v28, v29
	global_store_dwordx4 v162, v[24:27], s[4:5] nt
	v_mul_f32_e32 v20, 0xbfb8aa3b, v20
	v_mul_f32_e32 v16, 0xbfb8aa3b, v16
	v_mul_f32_e32 v21, 0xbfb8aa3b, v21
	v_mul_f32_e32 v17, 0xbfb8aa3b, v17
	v_mul_f32_e32 v22, 0xbfb8aa3b, v22
	v_mul_f32_e32 v18, 0xbfb8aa3b, v18
	v_mul_f32_e32 v19, 0xbfb8aa3b, v19
	v_mul_f32_e32 v23, 0xbfb8aa3b, v23
	v_exp_f32_e32 v20, v20
	v_exp_f32_e32 v16, v16
	v_exp_f32_e32 v21, v21
	v_exp_f32_e32 v17, v17
	v_exp_f32_e32 v22, v22
	v_exp_f32_e32 v18, v18
	v_exp_f32_e32 v19, v19
	v_exp_f32_e32 v23, v23
	v_add_f32_e32 v20, 1.0, v20
	v_add_f32_e32 v16, 1.0, v16
	v_add_f32_e32 v21, 1.0, v21
	v_add_f32_e32 v17, 1.0, v17
	v_add_f32_e32 v22, 1.0, v22
	v_add_f32_e32 v18, 1.0, v18
	v_add_f32_e32 v19, 1.0, v19
	v_add_f32_e32 v23, 1.0, v23
	v_rcp_f32_e32 v20, v20
	v_rcp_f32_e32 v16, v16
	v_rcp_f32_e32 v17, v17
	v_rcp_f32_e32 v22, v22
	v_rcp_f32_e32 v18, v18
	v_rcp_f32_e32 v19, v19
	v_rcp_f32_e32 v23, v23
	v_rcp_f32_e32 v21, v21
	s_nop 0
	v_cvt_pk_f16_f32 v19, v18, v19
	v_cvt_pk_f16_f32 v18, v16, v17
	v_cvt_pk_f16_f32 v17, v22, v23
	v_cvt_pk_f16_f32 v16, v20, v21
	global_store_dwordx4 v162, v[16:19], s[4:5] offset:256 nt
	v_mul_f32_e32 v12, 0xbfb8aa3b, v12
	v_mul_f32_e32 v8, 0xbfb8aa3b, v8
	v_mul_f32_e32 v13, 0xbfb8aa3b, v13
	v_mul_f32_e32 v9, 0xbfb8aa3b, v9
	v_mul_f32_e32 v14, 0xbfb8aa3b, v14
	v_mul_f32_e32 v10, 0xbfb8aa3b, v10
	v_mul_f32_e32 v11, 0xbfb8aa3b, v11
	v_mul_f32_e32 v15, 0xbfb8aa3b, v15
	v_exp_f32_e32 v12, v12
	v_exp_f32_e32 v8, v8
	v_exp_f32_e32 v13, v13
	v_exp_f32_e32 v9, v9
	v_exp_f32_e32 v14, v14
	v_exp_f32_e32 v10, v10
	v_exp_f32_e32 v11, v11
	v_exp_f32_e32 v15, v15
	v_add_f32_e32 v12, 1.0, v12
	v_add_f32_e32 v8, 1.0, v8
	v_add_f32_e32 v13, 1.0, v13
	v_add_f32_e32 v9, 1.0, v9
	v_add_f32_e32 v14, 1.0, v14
	v_add_f32_e32 v10, 1.0, v10
	v_add_f32_e32 v11, 1.0, v11
	v_add_f32_e32 v15, 1.0, v15
	v_rcp_f32_e32 v12, v12
	v_rcp_f32_e32 v8, v8
	v_rcp_f32_e32 v9, v9
	v_rcp_f32_e32 v14, v14
	v_rcp_f32_e32 v10, v10
	v_rcp_f32_e32 v11, v11
	v_rcp_f32_e32 v15, v15
	v_rcp_f32_e32 v13, v13
	s_nop 0
	v_cvt_pk_f16_f32 v11, v10, v11
	v_cvt_pk_f16_f32 v10, v8, v9
	v_cvt_pk_f16_f32 v9, v14, v15
	v_cvt_pk_f16_f32 v8, v12, v13
	global_store_dwordx4 v163, v[8:11], s[4:5] nt
	v_mul_f32_e32 v4, 0xbfb8aa3b, v4
	v_mul_f32_e32 v0, 0xbfb8aa3b, v0
	v_mul_f32_e32 v5, 0xbfb8aa3b, v5
	v_mul_f32_e32 v1, 0xbfb8aa3b, v1
	v_mul_f32_e32 v6, 0xbfb8aa3b, v6
	v_mul_f32_e32 v2, 0xbfb8aa3b, v2
	v_mul_f32_e32 v3, 0xbfb8aa3b, v3
	v_mul_f32_e32 v7, 0xbfb8aa3b, v7
	v_exp_f32_e32 v4, v4
	v_exp_f32_e32 v0, v0
	v_exp_f32_e32 v5, v5
	v_exp_f32_e32 v1, v1
	v_exp_f32_e32 v6, v6
	v_exp_f32_e32 v2, v2
	v_exp_f32_e32 v3, v3
	v_exp_f32_e32 v7, v7
	v_add_f32_e32 v4, 1.0, v4
	v_add_f32_e32 v0, 1.0, v0
	v_add_f32_e32 v5, 1.0, v5
	v_add_f32_e32 v1, 1.0, v1
	v_add_f32_e32 v6, 1.0, v6
	v_add_f32_e32 v2, 1.0, v2
	v_add_f32_e32 v3, 1.0, v3
	v_add_f32_e32 v7, 1.0, v7
	v_rcp_f32_e32 v4, v4
	v_rcp_f32_e32 v0, v0
	v_rcp_f32_e32 v1, v1
	v_rcp_f32_e32 v6, v6
	v_rcp_f32_e32 v2, v2
	v_rcp_f32_e32 v3, v3
	v_rcp_f32_e32 v7, v7
	v_rcp_f32_e32 v5, v5
	s_nop 0
	v_cvt_pk_f16_f32 v3, v2, v3
	v_cvt_pk_f16_f32 v2, v0, v1
	v_cvt_pk_f16_f32 v1, v6, v7
	v_cvt_pk_f16_f32 v0, v4, v5
	global_store_dwordx4 v163, v[0:3], s[4:5] offset:256 nt
	s_branch .LBB0_1145
.Lsh_k3:
	v_mov_b32_e32 v156, v136
	v_add_u32_e32 v157, 0x8000, v136
	v_add_u32_e32 v158, 0x10000, v136
	v_add_u32_e32 v159, 0x18000, v136
	v_add_u32_e32 v160, 0x40000, v136
	v_add_u32_e32 v161, 0x48000, v136
	v_add_u32_e32 v162, 0x50000, v136
	v_add_u32_e32 v163, 0x58000, v136
	global_load_dwordx4 v[164:167], v156, s[44:45]
	global_load_dwordx4 v[168:171], v156, s[44:45] offset:256
	global_load_dwordx4 v[172:175], v157, s[44:45]
	global_load_dwordx4 v[176:179], v157, s[44:45] offset:256
	global_load_dwordx4 v[180:183], v158, s[44:45]
	global_load_dwordx4 v[184:187], v158, s[44:45] offset:256
	global_load_dwordx4 v[188:191], v159, s[44:45]
	global_load_dwordx4 v[192:195], v159, s[44:45] offset:256
	s_waitcnt vmcnt(7)
	v_cvt_f32_f16_e32 v196, v164
	v_cvt_f32_f16_sdwa v197, v164 dst_sel:DWORD dst_unused:UNUSED_PAD src0_sel:WORD_1
	v_cvt_f32_f16_e32 v198, v165
	v_cvt_f32_f16_sdwa v199, v165 dst_sel:DWORD dst_unused:UNUSED_PAD src0_sel:WORD_1
	v_cvt_f32_f16_e32 v200, v166
	v_cvt_f32_f16_sdwa v201, v166 dst_sel:DWORD dst_unused:UNUSED_PAD src0_sel:WORD_1
	v_cvt_f32_f16_e32 v202, v167
	v_cvt_f32_f16_sdwa v203, v167 dst_sel:DWORD dst_unused:UNUSED_PAD src0_sel:WORD_1
	v_pk_mul_f32 v[124:125], v[124:125], v[196:197]
	v_pk_mul_f32 v[126:127], v[126:127], v[198:199]
	v_pk_mul_f32 v[120:121], v[120:121], v[200:201]
	v_pk_mul_f32 v[122:123], v[122:123], v[202:203]
	v_cvt_pk_f16_f32 v164, v124, v125
	v_cvt_pk_f16_f32 v165, v126, v127
	v_cvt_pk_f16_f32 v166, v120, v121
	v_cvt_pk_f16_f32 v167, v122, v123
	global_store_dwordx4 v156, v[164:167], s[44:45] nt
	s_nop 1
	global_load_dwordx4 v[164:167], v160, s[44:45]
	s_waitcnt vmcnt(8)
	v_cvt_f32_f16_e32 v196, v168
	v_cvt_f32_f16_sdwa v197, v168 dst_sel:DWORD dst_unused:UNUSED_PAD src0_sel:WORD_1
	v_cvt_f32_f16_e32 v198, v169
	v_cvt_f32_f16_sdwa v199, v169 dst_sel:DWORD dst_unused:UNUSED_PAD src0_sel:WORD_1
	v_cvt_f32_f16_e32 v200, v170
	v_cvt_f32_f16_sdwa v201, v170 dst_sel:DWORD dst_unused:UNUSED_PAD src0_sel:WORD_1
	v_cvt_f32_f16_e32 v202, v171
	v_cvt_f32_f16_sdwa v203, v171 dst_sel:DWORD dst_unused:UNUSED_PAD src0_sel:WORD_1
	v_pk_mul_f32 v[116:117], v[116:117], v[196:197]
	v_pk_mul_f32 v[118:119], v[118:119], v[198:199]
	v_pk_mul_f32 v[112:113], v[112:113], v[200:201]
	v_pk_mul_f32 v[114:115], v[114:115], v[202:203]
	v_cvt_pk_f16_f32 v168, v116, v117
	v_cvt_pk_f16_f32 v169, v118, v119
	v_cvt_pk_f16_f32 v170, v112, v113
	v_cvt_pk_f16_f32 v171, v114, v115
	global_store_dwordx4 v156, v[168:171], s[44:45] offset:256 nt
	s_nop 1
	global_load_dwordx4 v[168:171], v160, s[44:45] offset:256
	s_waitcnt vmcnt(9)
	v_cvt_f32_f16_e32 v196, v172
	v_cvt_f32_f16_sdwa v197, v172 dst_sel:DWORD dst_unused:UNUSED_PAD src0_sel:WORD_1
	v_cvt_f32_f16_e32 v198, v173
	v_cvt_f32_f16_sdwa v199, v173 dst_sel:DWORD dst_unused:UNUSED_PAD src0_sel:WORD_1
	v_cvt_f32_f16_e32 v200, v174
	v_cvt_f32_f16_sdwa v201, v174 dst_sel:DWORD dst_unused:UNUSED_PAD src0_sel:WORD_1
	v_cvt_f32_f16_e32 v202, v175
	v_cvt_f32_f16_sdwa v203, v175 dst_sel:DWORD dst_unused:UNUSED_PAD src0_sel:WORD_1
	v_pk_mul_f32 v[108:109], v[108:109], v[196:197]
	v_pk_mul_f32 v[110:111], v[110:111], v[198:199]
	v_pk_mul_f32 v[104:105], v[104:105], v[200:201]
	v_pk_mul_f32 v[106:107], v[106:107], v[202:203]
	v_cvt_pk_f16_f32 v172, v108, v109
	v_cvt_pk_f16_f32 v173, v110, v111
	v_cvt_pk_f16_f32 v174, v104, v105
	v_cvt_pk_f16_f32 v175, v106, v107
	global_store_dwordx4 v157, v[172:175], s[44:45] nt
	s_nop 1
	global_load_dwordx4 v[172:175], v161, s[44:45]
	s_waitcnt vmcnt(10)
	v_cvt_f32_f16_e32 v196, v176
	v_cvt_f32_f16_sdwa v197, v176 dst_sel:DWORD dst_unused:UNUSED_PAD src0_sel:WORD_1
	v_cvt_f32_f16_e32 v198, v177
	v_cvt_f32_f16_sdwa v199, v177 dst_sel:DWORD dst_unused:UNUSED_PAD src0_sel:WORD_1
	v_cvt_f32_f16_e32 v200, v178
	v_cvt_f32_f16_sdwa v201, v178 dst_sel:DWORD dst_unused:UNUSED_PAD src0_sel:WORD_1
	v_cvt_f32_f16_e32 v202, v179
	v_cvt_f32_f16_sdwa v203, v179 dst_sel:DWORD dst_unused:UNUSED_PAD src0_sel:WORD_1
	v_pk_mul_f32 v[100:101], v[100:101], v[196:197]
	v_pk_mul_f32 v[102:103], v[102:103], v[198:199]
	v_pk_mul_f32 v[96:97], v[96:97], v[200:201]
	v_pk_mul_f32 v[98:99], v[98:99], v[202:203]
	v_cvt_pk_f16_f32 v176, v100, v101
	v_cvt_pk_f16_f32 v177, v102, v103
	v_cvt_pk_f16_f32 v178, v96, v97
	v_cvt_pk_f16_f32 v179, v98, v99
	global_store_dwordx4 v157, v[176:179], s[44:45] offset:256 nt
	s_nop 1
	global_load_dwordx4 v[176:179], v161, s[44:45] offset:256
	s_waitcnt vmcnt(11)
	v_cvt_f32_f16_e32 v196, v180
	v_cvt_f32_f16_sdwa v197, v180 dst_sel:DWORD dst_unused:UNUSED_PAD src0_sel:WORD_1
	v_cvt_f32_f16_e32 v198, v181
	v_cvt_f32_f16_sdwa v199, v181 dst_sel:DWORD dst_unused:UNUSED_PAD src0_sel:WORD_1
	v_cvt_f32_f16_e32 v200, v182
	v_cvt_f32_f16_sdwa v201, v182 dst_sel:DWORD dst_unused:UNUSED_PAD src0_sel:WORD_1
	v_cvt_f32_f16_e32 v202, v183
	v_cvt_f32_f16_sdwa v203, v183 dst_sel:DWORD dst_unused:UNUSED_PAD src0_sel:WORD_1
	v_pk_mul_f32 v[92:93], v[92:93], v[196:197]
	v_pk_mul_f32 v[94:95], v[94:95], v[198:199]
	v_pk_mul_f32 v[88:89], v[88:89], v[200:201]
	v_pk_mul_f32 v[90:91], v[90:91], v[202:203]
	v_cvt_pk_f16_f32 v180, v92, v93
	v_cvt_pk_f16_f32 v181, v94, v95
	v_cvt_pk_f16_f32 v182, v88, v89
	v_cvt_pk_f16_f32 v183, v90, v91
	global_store_dwordx4 v158, v[180:183], s[44:45] nt
	s_nop 1
	global_load_dwordx4 v[180:183], v162, s[44:45]
	s_waitcnt vmcnt(12)
	v_cvt_f32_f16_e32 v196, v184
	v_cvt_f32_f16_sdwa v197, v184 dst_sel:DWORD dst_unused:UNUSED_PAD src0_sel:WORD_1
	v_cvt_f32_f16_e32 v198, v185
	v_cvt_f32_f16_sdwa v199, v185 dst_sel:DWORD dst_unused:UNUSED_PAD src0_sel:WORD_1
	v_cvt_f32_f16_e32 v200, v186
	v_cvt_f32_f16_sdwa v201, v186 dst_sel:DWORD dst_unused:UNUSED_PAD src0_sel:WORD_1
	v_cvt_f32_f16_e32 v202, v187
	v_cvt_f32_f16_sdwa v203, v187 dst_sel:DWORD dst_unused:UNUSED_PAD src0_sel:WORD_1
	v_pk_mul_f32 v[84:85], v[84:85], v[196:197]
	v_pk_mul_f32 v[86:87], v[86:87], v[198:199]
	v_pk_mul_f32 v[80:81], v[80:81], v[200:201]
	v_pk_mul_f32 v[82:83], v[82:83], v[202:203]
	v_cvt_pk_f16_f32 v184, v84, v85
	v_cvt_pk_f16_f32 v185, v86, v87
	v_cvt_pk_f16_f32 v186, v80, v81
	v_cvt_pk_f16_f32 v187, v82, v83
	global_store_dwordx4 v158, v[184:187], s[44:45] offset:256 nt
	s_nop 1
	global_load_dwordx4 v[184:187], v162, s[44:45] offset:256
	s_waitcnt vmcnt(13)
	v_cvt_f32_f16_e32 v196, v188
	v_cvt_f32_f16_sdwa v197, v188 dst_sel:DWORD dst_unused:UNUSED_PAD src0_sel:WORD_1
	v_cvt_f32_f16_e32 v198, v189
	v_cvt_f32_f16_sdwa v199, v189 dst_sel:DWORD dst_unused:UNUSED_PAD src0_sel:WORD_1
	v_cvt_f32_f16_e32 v200, v190
	v_cvt_f32_f16_sdwa v201, v190 dst_sel:DWORD dst_unused:UNUSED_PAD src0_sel:WORD_1
	v_cvt_f32_f16_e32 v202, v191
	v_cvt_f32_f16_sdwa v203, v191 dst_sel:DWORD dst_unused:UNUSED_PAD src0_sel:WORD_1
	v_pk_mul_f32 v[76:77], v[76:77], v[196:197]
	v_pk_mul_f32 v[78:79], v[78:79], v[198:199]
	v_pk_mul_f32 v[72:73], v[72:73], v[200:201]
	v_pk_mul_f32 v[74:75], v[74:75], v[202:203]
	v_cvt_pk_f16_f32 v188, v76, v77
	v_cvt_pk_f16_f32 v189, v78, v79
	v_cvt_pk_f16_f32 v190, v72, v73
	v_cvt_pk_f16_f32 v191, v74, v75
	global_store_dwordx4 v159, v[188:191], s[44:45] nt
	s_nop 1
	global_load_dwordx4 v[188:191], v163, s[44:45]
	s_waitcnt vmcnt(14)
	v_cvt_f32_f16_e32 v196, v192
	v_cvt_f32_f16_sdwa v197, v192 dst_sel:DWORD dst_unused:UNUSED_PAD src0_sel:WORD_1
	v_cvt_f32_f16_e32 v198, v193
	v_cvt_f32_f16_sdwa v199, v193 dst_sel:DWORD dst_unused:UNUSED_PAD src0_sel:WORD_1
	v_cvt_f32_f16_e32 v200, v194
	v_cvt_f32_f16_sdwa v201, v194 dst_sel:DWORD dst_unused:UNUSED_PAD src0_sel:WORD_1
	v_cvt_f32_f16_e32 v202, v195
	v_cvt_f32_f16_sdwa v203, v195 dst_sel:DWORD dst_unused:UNUSED_PAD src0_sel:WORD_1
	v_pk_mul_f32 v[68:69], v[68:69], v[196:197]
	v_pk_mul_f32 v[70:71], v[70:71], v[198:199]
	v_pk_mul_f32 v[64:65], v[64:65], v[200:201]
	v_pk_mul_f32 v[66:67], v[66:67], v[202:203]
	v_cvt_pk_f16_f32 v192, v68, v69
	v_cvt_pk_f16_f32 v193, v70, v71
	v_cvt_pk_f16_f32 v194, v64, v65
	v_cvt_pk_f16_f32 v195, v66, v67
	global_store_dwordx4 v159, v[192:195], s[44:45] offset:256 nt
	s_nop 1
	global_load_dwordx4 v[192:195], v163, s[44:45] offset:256
	s_waitcnt vmcnt(14)
	v_cvt_f32_f16_e32 v196, v164
	v_cvt_f32_f16_sdwa v197, v164 dst_sel:DWORD dst_unused:UNUSED_PAD src0_sel:WORD_1
	v_cvt_f32_f16_e32 v198, v165
	v_cvt_f32_f16_sdwa v199, v165 dst_sel:DWORD dst_unused:UNUSED_PAD src0_sel:WORD_1
	v_cvt_f32_f16_e32 v200, v166
	v_cvt_f32_f16_sdwa v201, v166 dst_sel:DWORD dst_unused:UNUSED_PAD src0_sel:WORD_1
	v_cvt_f32_f16_e32 v202, v167
	v_cvt_f32_f16_sdwa v203, v167 dst_sel:DWORD dst_unused:UNUSED_PAD src0_sel:WORD_1
	v_pk_mul_f32 v[60:61], v[60:61], v[196:197]
	v_pk_mul_f32 v[62:63], v[62:63], v[198:199]
	v_pk_mul_f32 v[56:57], v[56:57], v[200:201]
	v_pk_mul_f32 v[58:59], v[58:59], v[202:203]
	v_cvt_pk_f16_f32 v164, v60, v61
	v_cvt_pk_f16_f32 v165, v62, v63
	v_cvt_pk_f16_f32 v166, v56, v57
	v_cvt_pk_f16_f32 v167, v58, v59
	global_store_dwordx4 v160, v[164:167], s[44:45] nt
	s_nop 1
	s_waitcnt vmcnt(13)
	v_cvt_f32_f16_e32 v196, v168
	v_cvt_f32_f16_sdwa v197, v168 dst_sel:DWORD dst_unused:UNUSED_PAD src0_sel:WORD_1
	v_cvt_f32_f16_e32 v198, v169
	v_cvt_f32_f16_sdwa v199, v169 dst_sel:DWORD dst_unused:UNUSED_PAD src0_sel:WORD_1
	v_cvt_f32_f16_e32 v200, v170
	v_cvt_f32_f16_sdwa v201, v170 dst_sel:DWORD dst_unused:UNUSED_PAD src0_sel:WORD_1
	v_cvt_f32_f16_e32 v202, v171
	v_cvt_f32_f16_sdwa v203, v171 dst_sel:DWORD dst_unused:UNUSED_PAD src0_sel:WORD_1
	v_pk_mul_f32 v[52:53], v[52:53], v[196:197]
	v_pk_mul_f32 v[54:55], v[54:55], v[198:199]
	v_pk_mul_f32 v[48:49], v[48:49], v[200:201]
	v_pk_mul_f32 v[50:51], v[50:51], v[202:203]
	v_cvt_pk_f16_f32 v168, v52, v53
	v_cvt_pk_f16_f32 v169, v54, v55
	v_cvt_pk_f16_f32 v170, v48, v49
	v_cvt_pk_f16_f32 v171, v50, v51
	global_store_dwordx4 v160, v[168:171], s[44:45] offset:256 nt
	s_nop 1
	s_waitcnt vmcnt(12)
	v_cvt_f32_f16_e32 v196, v172
	v_cvt_f32_f16_sdwa v197, v172 dst_sel:DWORD dst_unused:UNUSED_PAD src0_sel:WORD_1
	v_cvt_f32_f16_e32 v198, v173
	v_cvt_f32_f16_sdwa v199, v173 dst_sel:DWORD dst_unused:UNUSED_PAD src0_sel:WORD_1
	v_cvt_f32_f16_e32 v200, v174
	v_cvt_f32_f16_sdwa v201, v174 dst_sel:DWORD dst_unused:UNUSED_PAD src0_sel:WORD_1
	v_cvt_f32_f16_e32 v202, v175
	v_cvt_f32_f16_sdwa v203, v175 dst_sel:DWORD dst_unused:UNUSED_PAD src0_sel:WORD_1
	v_pk_mul_f32 v[44:45], v[44:45], v[196:197]
	v_pk_mul_f32 v[46:47], v[46:47], v[198:199]
	v_pk_mul_f32 v[40:41], v[40:41], v[200:201]
	v_pk_mul_f32 v[42:43], v[42:43], v[202:203]
	v_cvt_pk_f16_f32 v172, v44, v45
	v_cvt_pk_f16_f32 v173, v46, v47
	v_cvt_pk_f16_f32 v174, v40, v41
	v_cvt_pk_f16_f32 v175, v42, v43
	global_store_dwordx4 v161, v[172:175], s[44:45] nt
	s_nop 1
	s_waitcnt vmcnt(11)
	v_cvt_f32_f16_e32 v196, v176
	v_cvt_f32_f16_sdwa v197, v176 dst_sel:DWORD dst_unused:UNUSED_PAD src0_sel:WORD_1
	v_cvt_f32_f16_e32 v198, v177
	v_cvt_f32_f16_sdwa v199, v177 dst_sel:DWORD dst_unused:UNUSED_PAD src0_sel:WORD_1
	v_cvt_f32_f16_e32 v200, v178
	v_cvt_f32_f16_sdwa v201, v178 dst_sel:DWORD dst_unused:UNUSED_PAD src0_sel:WORD_1
	v_cvt_f32_f16_e32 v202, v179
	v_cvt_f32_f16_sdwa v203, v179 dst_sel:DWORD dst_unused:UNUSED_PAD src0_sel:WORD_1
	v_pk_mul_f32 v[36:37], v[36:37], v[196:197]
	v_pk_mul_f32 v[38:39], v[38:39], v[198:199]
	v_pk_mul_f32 v[32:33], v[32:33], v[200:201]
	v_pk_mul_f32 v[34:35], v[34:35], v[202:203]
	v_cvt_pk_f16_f32 v176, v36, v37
	v_cvt_pk_f16_f32 v177, v38, v39
	v_cvt_pk_f16_f32 v178, v32, v33
	v_cvt_pk_f16_f32 v179, v34, v35
	global_store_dwordx4 v161, v[176:179], s[44:45] offset:256 nt
	s_nop 1
	s_waitcnt vmcnt(10)
	v_cvt_f32_f16_e32 v196, v180
	v_cvt_f32_f16_sdwa v197, v180 dst_sel:DWORD dst_unused:UNUSED_PAD src0_sel:WORD_1
	v_cvt_f32_f16_e32 v198, v181
	v_cvt_f32_f16_sdwa v199, v181 dst_sel:DWORD dst_unused:UNUSED_PAD src0_sel:WORD_1
	v_cvt_f32_f16_e32 v200, v182
	v_cvt_f32_f16_sdwa v201, v182 dst_sel:DWORD dst_unused:UNUSED_PAD src0_sel:WORD_1
	v_cvt_f32_f16_e32 v202, v183
	v_cvt_f32_f16_sdwa v203, v183 dst_sel:DWORD dst_unused:UNUSED_PAD src0_sel:WORD_1
	v_pk_mul_f32 v[28:29], v[28:29], v[196:197]
	v_pk_mul_f32 v[30:31], v[30:31], v[198:199]
	v_pk_mul_f32 v[24:25], v[24:25], v[200:201]
	v_pk_mul_f32 v[26:27], v[26:27], v[202:203]
	v_cvt_pk_f16_f32 v180, v28, v29
	v_cvt_pk_f16_f32 v181, v30, v31
	v_cvt_pk_f16_f32 v182, v24, v25
	v_cvt_pk_f16_f32 v183, v26, v27
	global_store_dwordx4 v162, v[180:183], s[44:45] nt
	s_nop 1
	s_waitcnt vmcnt(9)
	v_cvt_f32_f16_e32 v196, v184
	v_cvt_f32_f16_sdwa v197, v184 dst_sel:DWORD dst_unused:UNUSED_PAD src0_sel:WORD_1
	v_cvt_f32_f16_e32 v198, v185
	v_cvt_f32_f16_sdwa v199, v185 dst_sel:DWORD dst_unused:UNUSED_PAD src0_sel:WORD_1
	v_cvt_f32_f16_e32 v200, v186
	v_cvt_f32_f16_sdwa v201, v186 dst_sel:DWORD dst_unused:UNUSED_PAD src0_sel:WORD_1
	v_cvt_f32_f16_e32 v202, v187
	v_cvt_f32_f16_sdwa v203, v187 dst_sel:DWORD dst_unused:UNUSED_PAD src0_sel:WORD_1
	v_pk_mul_f32 v[20:21], v[20:21], v[196:197]
	v_pk_mul_f32 v[22:23], v[22:23], v[198:199]
	v_pk_mul_f32 v[16:17], v[16:17], v[200:201]
	v_pk_mul_f32 v[18:19], v[18:19], v[202:203]
	v_cvt_pk_f16_f32 v184, v20, v21
	v_cvt_pk_f16_f32 v185, v22, v23
	v_cvt_pk_f16_f32 v186, v16, v17
	v_cvt_pk_f16_f32 v187, v18, v19
	global_store_dwordx4 v162, v[184:187], s[44:45] offset:256 nt
	s_nop 1
	s_waitcnt vmcnt(8)
	v_cvt_f32_f16_e32 v196, v188
	v_cvt_f32_f16_sdwa v197, v188 dst_sel:DWORD dst_unused:UNUSED_PAD src0_sel:WORD_1
	v_cvt_f32_f16_e32 v198, v189
	v_cvt_f32_f16_sdwa v199, v189 dst_sel:DWORD dst_unused:UNUSED_PAD src0_sel:WORD_1
	v_cvt_f32_f16_e32 v200, v190
	v_cvt_f32_f16_sdwa v201, v190 dst_sel:DWORD dst_unused:UNUSED_PAD src0_sel:WORD_1
	v_cvt_f32_f16_e32 v202, v191
	v_cvt_f32_f16_sdwa v203, v191 dst_sel:DWORD dst_unused:UNUSED_PAD src0_sel:WORD_1
	v_pk_mul_f32 v[12:13], v[12:13], v[196:197]
	v_pk_mul_f32 v[14:15], v[14:15], v[198:199]
	v_pk_mul_f32 v[8:9], v[8:9], v[200:201]
	v_pk_mul_f32 v[10:11], v[10:11], v[202:203]
	v_cvt_pk_f16_f32 v188, v12, v13
	v_cvt_pk_f16_f32 v189, v14, v15
	v_cvt_pk_f16_f32 v190, v8, v9
	v_cvt_pk_f16_f32 v191, v10, v11
	global_store_dwordx4 v163, v[188:191], s[44:45] nt
	s_nop 1
	s_waitcnt vmcnt(7)
	v_cvt_f32_f16_e32 v196, v192
	v_cvt_f32_f16_sdwa v197, v192 dst_sel:DWORD dst_unused:UNUSED_PAD src0_sel:WORD_1
	v_cvt_f32_f16_e32 v198, v193
	v_cvt_f32_f16_sdwa v199, v193 dst_sel:DWORD dst_unused:UNUSED_PAD src0_sel:WORD_1
	v_cvt_f32_f16_e32 v200, v194
	v_cvt_f32_f16_sdwa v201, v194 dst_sel:DWORD dst_unused:UNUSED_PAD src0_sel:WORD_1
	v_cvt_f32_f16_e32 v202, v195
	v_cvt_f32_f16_sdwa v203, v195 dst_sel:DWORD dst_unused:UNUSED_PAD src0_sel:WORD_1
	v_pk_mul_f32 v[4:5], v[4:5], v[196:197]
	v_pk_mul_f32 v[6:7], v[6:7], v[198:199]
	v_pk_mul_f32 v[0:1], v[0:1], v[200:201]
	v_pk_mul_f32 v[2:3], v[2:3], v[202:203]
	v_cvt_pk_f16_f32 v192, v4, v5
	v_cvt_pk_f16_f32 v193, v6, v7
	v_cvt_pk_f16_f32 v194, v0, v1
	v_cvt_pk_f16_f32 v195, v2, v3
	global_store_dwordx4 v163, v[192:195], s[44:45] offset:256 nt
	s_nop 1
	s_branch .LBB0_1145

.LBB0_1536:
	s_or_b64 exec, exec, s[50:51]
	s_waitcnt vmcnt(0) lgkmcnt(0)
	s_barrier
	v_lshl_add_u32 v136, v155, 2, s79
	v_lshl_add_u32 v142, v154, 3, s70
	v_readlane_b32 s88, v255, 0
	v_readlane_b32 s89, v255, 1
	v_readlane_b32 s90, v255, 2
	v_readlane_b32 s91, v255, 3
	v_readlane_b32 s92, v255, 4
	v_readlane_b32 s93, v255, 5
	v_readlane_b32 s94, v255, 6
	v_readlane_b32 s95, v255, 7
	ds_read_b32 v190, v136
	ds_read_b32 v192, v136 offset:64
	ds_read_b32 v194, v136 offset:128
	ds_read_b32 v196, v136 offset:192
	ds_read_b32 v198, v136 offset:512
	ds_read_b32 v200, v136 offset:576
	ds_read_b32 v202, v136 offset:640
	ds_read_b32 v204, v136 offset:704
	v_lshl_add_u32 v154, s30, 8, v142
	s_waitcnt lgkmcnt(7)
	s_and_saveexec_b64 s[22:23], s[6:7]
	v_pk_mul_f32 v[126:127], v[126:127], v[190:191] op_sel_hi:[1,0]
	v_pk_mul_f32 v[124:125], v[124:125], v[190:191] op_sel_hi:[1,0]
	v_pk_mul_f32 v[118:119], v[118:119], v[190:191] op_sel_hi:[1,0]
	v_pk_mul_f32 v[116:117], v[116:117], v[190:191] op_sel_hi:[1,0]
	v_pk_mul_f32 v[122:123], v[122:123], v[190:191] op_sel_hi:[1,0]
	v_pk_mul_f32 v[120:121], v[120:121], v[190:191] op_sel_hi:[1,0]
	v_pk_mul_f32 v[114:115], v[114:115], v[190:191] op_sel_hi:[1,0]
	v_pk_mul_f32 v[112:113], v[112:113], v[190:191] op_sel_hi:[1,0]
	v_lshlrev_b32_e32 v143, 12, v153
	v_lshl_add_u32 v152, v154, 2, v143
	v_pk_mul_f32 v[124:125], v[174:175], v[124:125]
	v_pk_mul_f32 v[126:127], v[176:177], v[126:127]
	v_pk_mul_f32 v[116:117], v[178:179], v[116:117]
	v_pk_mul_f32 v[118:119], v[180:181], v[118:119]
	v_pk_mul_f32 v[120:121], v[182:183], v[120:121]
	v_pk_mul_f32 v[122:123], v[184:185], v[122:123]
	v_pk_mul_f32 v[112:113], v[186:187], v[112:113]
	v_pk_mul_f32 v[114:115], v[188:189], v[114:115]
	global_store_dwordx4 v152, v[124:127], s[94:95] nt
	global_store_dwordx4 v152, v[116:119], s[94:95] offset:16 nt
	global_store_dwordx4 v152, v[120:123], s[94:95] offset:512 nt
	global_store_dwordx4 v152, v[112:115], s[94:95] offset:528 nt
	s_mov_b64 exec, s[22:23]
	s_waitcnt lgkmcnt(6)
	s_and_saveexec_b64 s[22:23], s[8:9]
	v_pk_mul_f32 v[110:111], v[110:111], v[192:193] op_sel_hi:[1,0]
	v_pk_mul_f32 v[108:109], v[108:109], v[192:193] op_sel_hi:[1,0]
	v_pk_mul_f32 v[102:103], v[102:103], v[192:193] op_sel_hi:[1,0]
	v_pk_mul_f32 v[100:101], v[100:101], v[192:193] op_sel_hi:[1,0]
	v_pk_mul_f32 v[106:107], v[106:107], v[192:193] op_sel_hi:[1,0]
	v_pk_mul_f32 v[104:105], v[104:105], v[192:193] op_sel_hi:[1,0]
	v_pk_mul_f32 v[98:99], v[98:99], v[192:193] op_sel_hi:[1,0]
	v_pk_mul_f32 v[96:97], v[96:97], v[192:193] op_sel_hi:[1,0]
	v_lshlrev_b32_e32 v143, 12, v156
	v_lshl_add_u32 v152, v154, 2, v143
	v_pk_mul_f32 v[108:109], v[174:175], v[108:109]
	v_pk_mul_f32 v[110:111], v[176:177], v[110:111]
	v_pk_mul_f32 v[100:101], v[178:179], v[100:101]
	v_pk_mul_f32 v[102:103], v[180:181], v[102:103]
	v_pk_mul_f32 v[104:105], v[182:183], v[104:105]
	v_pk_mul_f32 v[106:107], v[184:185], v[106:107]
	v_pk_mul_f32 v[96:97], v[186:187], v[96:97]
	v_pk_mul_f32 v[98:99], v[188:189], v[98:99]
	global_store_dwordx4 v152, v[108:111], s[94:95] nt
	global_store_dwordx4 v152, v[100:103], s[94:95] offset:16 nt
	global_store_dwordx4 v152, v[104:107], s[94:95] offset:512 nt
	global_store_dwordx4 v152, v[96:99], s[94:95] offset:528 nt
	s_mov_b64 exec, s[22:23]
	s_waitcnt lgkmcnt(5)
	s_and_saveexec_b64 s[22:23], s[10:11]
	v_pk_mul_f32 v[94:95], v[94:95], v[194:195] op_sel_hi:[1,0]
	v_pk_mul_f32 v[92:93], v[92:93], v[194:195] op_sel_hi:[1,0]
	v_pk_mul_f32 v[86:87], v[86:87], v[194:195] op_sel_hi:[1,0]
	v_pk_mul_f32 v[84:85], v[84:85], v[194:195] op_sel_hi:[1,0]
	v_pk_mul_f32 v[90:91], v[90:91], v[194:195] op_sel_hi:[1,0]
	v_pk_mul_f32 v[88:89], v[88:89], v[194:195] op_sel_hi:[1,0]
	v_pk_mul_f32 v[82:83], v[82:83], v[194:195] op_sel_hi:[1,0]
	v_pk_mul_f32 v[80:81], v[80:81], v[194:195] op_sel_hi:[1,0]
	v_lshlrev_b32_e32 v143, 12, v157
	v_lshl_add_u32 v152, v154, 2, v143
	v_pk_mul_f32 v[92:93], v[174:175], v[92:93]
	v_pk_mul_f32 v[94:95], v[176:177], v[94:95]
	v_pk_mul_f32 v[84:85], v[178:179], v[84:85]
	v_pk_mul_f32 v[86:87], v[180:181], v[86:87]
	v_pk_mul_f32 v[88:89], v[182:183], v[88:89]
	v_pk_mul_f32 v[90:91], v[184:185], v[90:91]
	v_pk_mul_f32 v[80:81], v[186:187], v[80:81]
	v_pk_mul_f32 v[82:83], v[188:189], v[82:83]
	global_store_dwordx4 v152, v[92:95], s[94:95] nt
	global_store_dwordx4 v152, v[84:87], s[94:95] offset:16 nt
	global_store_dwordx4 v152, v[88:91], s[94:95] offset:512 nt
	global_store_dwordx4 v152, v[80:83], s[94:95] offset:528 nt
	s_mov_b64 exec, s[22:23]
	s_waitcnt lgkmcnt(4)
	s_and_saveexec_b64 s[22:23], s[12:13]
	v_pk_mul_f32 v[78:79], v[78:79], v[196:197] op_sel_hi:[1,0]
	v_pk_mul_f32 v[76:77], v[76:77], v[196:197] op_sel_hi:[1,0]
	v_pk_mul_f32 v[70:71], v[70:71], v[196:197] op_sel_hi:[1,0]
	v_pk_mul_f32 v[68:69], v[68:69], v[196:197] op_sel_hi:[1,0]
	v_pk_mul_f32 v[74:75], v[74:75], v[196:197] op_sel_hi:[1,0]
	v_pk_mul_f32 v[72:73], v[72:73], v[196:197] op_sel_hi:[1,0]
	v_pk_mul_f32 v[66:67], v[66:67], v[196:197] op_sel_hi:[1,0]
	v_pk_mul_f32 v[64:65], v[64:65], v[196:197] op_sel_hi:[1,0]
	v_lshlrev_b32_e32 v143, 12, v158
	v_lshl_add_u32 v152, v154, 2, v143
	v_pk_mul_f32 v[76:77], v[174:175], v[76:77]
	v_pk_mul_f32 v[78:79], v[176:177], v[78:79]
	v_pk_mul_f32 v[68:69], v[178:179], v[68:69]
	v_pk_mul_f32 v[70:71], v[180:181], v[70:71]
	v_pk_mul_f32 v[72:73], v[182:183], v[72:73]
	v_pk_mul_f32 v[74:75], v[184:185], v[74:75]
	v_pk_mul_f32 v[64:65], v[186:187], v[64:65]
	v_pk_mul_f32 v[66:67], v[188:189], v[66:67]
	global_store_dwordx4 v152, v[76:79], s[94:95] nt
	global_store_dwordx4 v152, v[68:71], s[94:95] offset:16 nt
	global_store_dwordx4 v152, v[72:75], s[94:95] offset:512 nt
	global_store_dwordx4 v152, v[64:67], s[94:95] offset:528 nt
	s_mov_b64 exec, s[22:23]
	s_waitcnt lgkmcnt(3)
	s_and_saveexec_b64 s[22:23], s[14:15]
	v_pk_mul_f32 v[62:63], v[62:63], v[198:199] op_sel_hi:[1,0]
	v_pk_mul_f32 v[60:61], v[60:61], v[198:199] op_sel_hi:[1,0]
	v_pk_mul_f32 v[54:55], v[54:55], v[198:199] op_sel_hi:[1,0]
	v_pk_mul_f32 v[52:53], v[52:53], v[198:199] op_sel_hi:[1,0]
	v_pk_mul_f32 v[58:59], v[58:59], v[198:199] op_sel_hi:[1,0]
	v_pk_mul_f32 v[56:57], v[56:57], v[198:199] op_sel_hi:[1,0]
	v_pk_mul_f32 v[50:51], v[50:51], v[198:199] op_sel_hi:[1,0]
	v_pk_mul_f32 v[48:49], v[48:49], v[198:199] op_sel_hi:[1,0]
	v_lshlrev_b32_e32 v143, 12, v159
	v_lshl_add_u32 v152, v154, 2, v143
	v_pk_mul_f32 v[60:61], v[174:175], v[60:61]
	v_pk_mul_f32 v[62:63], v[176:177], v[62:63]
	v_pk_mul_f32 v[52:53], v[178:179], v[52:53]
	v_pk_mul_f32 v[54:55], v[180:181], v[54:55]
	v_pk_mul_f32 v[56:57], v[182:183], v[56:57]
	v_pk_mul_f32 v[58:59], v[184:185], v[58:59]
	v_pk_mul_f32 v[48:49], v[186:187], v[48:49]
	v_pk_mul_f32 v[50:51], v[188:189], v[50:51]
	global_store_dwordx4 v152, v[60:63], s[94:95] nt
	global_store_dwordx4 v152, v[52:55], s[94:95] offset:16 nt
	global_store_dwordx4 v152, v[56:59], s[94:95] offset:512 nt
	global_store_dwordx4 v152, v[48:51], s[94:95] offset:528 nt
	s_mov_b64 exec, s[22:23]
	s_waitcnt lgkmcnt(2)
	s_and_saveexec_b64 s[22:23], s[16:17]
	v_pk_mul_f32 v[46:47], v[46:47], v[200:201] op_sel_hi:[1,0]
	v_pk_mul_f32 v[44:45], v[44:45], v[200:201] op_sel_hi:[1,0]
	v_pk_mul_f32 v[38:39], v[38:39], v[200:201] op_sel_hi:[1,0]
	v_pk_mul_f32 v[36:37], v[36:37], v[200:201] op_sel_hi:[1,0]
	v_pk_mul_f32 v[42:43], v[42:43], v[200:201] op_sel_hi:[1,0]
	v_pk_mul_f32 v[40:41], v[40:41], v[200:201] op_sel_hi:[1,0]
	v_pk_mul_f32 v[34:35], v[34:35], v[200:201] op_sel_hi:[1,0]
	v_pk_mul_f32 v[32:33], v[32:33], v[200:201] op_sel_hi:[1,0]
	v_lshlrev_b32_e32 v143, 12, v162
	v_lshl_add_u32 v152, v154, 2, v143
	v_pk_mul_f32 v[44:45], v[174:175], v[44:45]
	v_pk_mul_f32 v[46:47], v[176:177], v[46:47]
	v_pk_mul_f32 v[36:37], v[178:179], v[36:37]
	v_pk_mul_f32 v[38:39], v[180:181], v[38:39]
	v_pk_mul_f32 v[40:41], v[182:183], v[40:41]
	v_pk_mul_f32 v[42:43], v[184:185], v[42:43]
	v_pk_mul_f32 v[32:33], v[186:187], v[32:33]
	v_pk_mul_f32 v[34:35], v[188:189], v[34:35]
	global_store_dwordx4 v152, v[44:47], s[94:95] nt
	global_store_dwordx4 v152, v[36:39], s[94:95] offset:16 nt
	global_store_dwordx4 v152, v[40:43], s[94:95] offset:512 nt
	global_store_dwordx4 v152, v[32:35], s[94:95] offset:528 nt
	s_mov_b64 exec, s[22:23]
	s_waitcnt lgkmcnt(1)
	s_and_saveexec_b64 s[22:23], s[18:19]
	v_pk_mul_f32 v[30:31], v[30:31], v[202:203] op_sel_hi:[1,0]
	v_pk_mul_f32 v[28:29], v[28:29], v[202:203] op_sel_hi:[1,0]
	v_pk_mul_f32 v[22:23], v[22:23], v[202:203] op_sel_hi:[1,0]
	v_pk_mul_f32 v[20:21], v[20:21], v[202:203] op_sel_hi:[1,0]
	v_pk_mul_f32 v[26:27], v[26:27], v[202:203] op_sel_hi:[1,0]
	v_pk_mul_f32 v[24:25], v[24:25], v[202:203] op_sel_hi:[1,0]
	v_pk_mul_f32 v[18:19], v[18:19], v[202:203] op_sel_hi:[1,0]
	v_pk_mul_f32 v[16:17], v[16:17], v[202:203] op_sel_hi:[1,0]
	v_lshlrev_b32_e32 v143, 12, v163
	v_lshl_add_u32 v152, v154, 2, v143
	v_pk_mul_f32 v[28:29], v[174:175], v[28:29]
	v_pk_mul_f32 v[30:31], v[176:177], v[30:31]
	v_pk_mul_f32 v[20:21], v[178:179], v[20:21]
	v_pk_mul_f32 v[22:23], v[180:181], v[22:23]
	v_pk_mul_f32 v[24:25], v[182:183], v[24:25]
	v_pk_mul_f32 v[26:27], v[184:185], v[26:27]
	v_pk_mul_f32 v[16:17], v[186:187], v[16:17]
	v_pk_mul_f32 v[18:19], v[188:189], v[18:19]
	global_store_dwordx4 v152, v[28:31], s[94:95] nt
	global_store_dwordx4 v152, v[20:23], s[94:95] offset:16 nt
	global_store_dwordx4 v152, v[24:27], s[94:95] offset:512 nt
	global_store_dwordx4 v152, v[16:19], s[94:95] offset:528 nt
	s_mov_b64 exec, s[22:23]
	s_waitcnt lgkmcnt(0)
	s_and_saveexec_b64 s[22:23], s[20:21]
	v_pk_mul_f32 v[14:15], v[14:15], v[204:205] op_sel_hi:[1,0]
	v_pk_mul_f32 v[12:13], v[12:13], v[204:205] op_sel_hi:[1,0]
	v_pk_mul_f32 v[6:7], v[6:7], v[204:205] op_sel_hi:[1,0]
	v_pk_mul_f32 v[4:5], v[4:5], v[204:205] op_sel_hi:[1,0]
	v_pk_mul_f32 v[10:11], v[10:11], v[204:205] op_sel_hi:[1,0]
	v_pk_mul_f32 v[8:9], v[8:9], v[204:205] op_sel_hi:[1,0]
	v_pk_mul_f32 v[2:3], v[2:3], v[204:205] op_sel_hi:[1,0]
	v_pk_mul_f32 v[0:1], v[0:1], v[204:205] op_sel_hi:[1,0]
	v_lshlrev_b32_e32 v143, 12, v164
	v_lshl_add_u32 v152, v154, 2, v143
	v_pk_mul_f32 v[12:13], v[174:175], v[12:13]
	v_pk_mul_f32 v[14:15], v[176:177], v[14:15]
	v_pk_mul_f32 v[4:5], v[178:179], v[4:5]
	v_pk_mul_f32 v[6:7], v[180:181], v[6:7]
	v_pk_mul_f32 v[8:9], v[182:183], v[8:9]
	v_pk_mul_f32 v[10:11], v[184:185], v[10:11]
	v_pk_mul_f32 v[0:1], v[186:187], v[0:1]
	v_pk_mul_f32 v[2:3], v[188:189], v[2:3]
	global_store_dwordx4 v152, v[12:15], s[94:95] nt
	global_store_dwordx4 v152, v[4:7], s[94:95] offset:16 nt
	global_store_dwordx4 v152, v[8:11], s[94:95] offset:512 nt
	global_store_dwordx4 v152, v[0:3], s[94:95] offset:528 nt
	s_mov_b64 exec, s[22:23]
	s_waitcnt lgkmcnt(0)
	s_barrier
	s_andn2_b64 vcc, exec, s[4:5]
	s_mov_b64 s[4:5], -1
	s_cbranch_vccnz .LBB0_1462
	s_and_b64 vcc, exec, s[0:1]
	s_cbranch_vccnz .LBB0_1461
	s_barrier
	s_branch .LBB0_1461
